# static s_setprio 1 for waves 4-7 around each GEMM K-loop, hipcc per-phase priority flips removed
# speedup vs baseline: 1.0202x; 1.0202x over previous
; #define PG8_STAGE(bufoff, gbase, voff) do { _Pragma("unroll") for (int _i = 0; _i < 2; ++_i) \
;         __builtin_amdgcn_global_load_lds((const unsigned*)((const char*)(gbase) + (voff)[_i]), (PG8_LAS unsigned*)(lds + (bufoff) + ldsw + _i * 8192), 16, 0, 0); } while (0)
; #define PG8_LDA(dst, b, h) do { _Pragma("unroll") for (int m = 0; m < 4; ++m) _Pragma("unroll") for (int k = 0; k < 2; ++k) dst[m][k] = *(const PG8_LAS bf16x8*)(lds + PG8_SA(b, h) + aoff + m * 2048 + k * 1024); } while (0)
; #define PG8_LDB(dst, b, h) do { _Pragma("unroll") for (int n = 0; n < 2; ++n) _Pragma("unroll") for (int k = 0; k < 2; ++k) dst[n][k] = *(const PG8_LAS bf16x8*)(lds + PG8_SB(b, h) + boff + n * 2048 + k * 1024); } while (0)
; #define PG8_WAIT_V(n) asm volatile("s_waitcnt vmcnt(" #n ")" ::: "memory")
; #define PG8_WAIT_L(n) asm volatile("s_waitcnt lgkmcnt(" #n ")" ::: "memory")
; #define PG8_BAR __builtin_amdgcn_s_barrier()
; template <class Epi, class Sched, bool ALIGN_EPI = false, bool SP2 = false>
; __device__ __forceinline__ void gemm_phase(PG8_LAS unsigned char* lds, const Gemm g, const Sched& S, const Epi& E, const int tid) {
;     ...
;     for (;;) {
;         const bool has_next = S.next(ui + 1, nxt);
;         const char* nA = has_next ? (const char*)g.A + (size_t)nxt.pm * tstep : cA; const char* nB = has_next ? (const char*)g.Bt + (size_t)nxt.pn * tstep : cB;
;         for (int t = 0; t < nt; t += 2) {
;             const bool last = (t == nt - 2);
;             const char* a1 = cA + (size_t)(t + 1) * kstep;
;             const char* a2 = last ? nA : cA + (size_t)(t + 2) * kstep; const char* b2 = last ? nB : cB + (size_t)(t + 2) * kstep;
;             const char* a3 = a2 + kstep; const char* b3 = b2 + kstep;
;             if (last && has_next) S.a_ready(nxt);
;             if constexpr (SP2) {
;             PG8_LDB(B0, 0, 0); PG8_LDB(B1, 0, 1); PG8_SCHED; PG8_LDA(At, 0, 0); PG8_STAGE(PG8_SA(1, 1), a1 + hstep, voffA);
;             PG8_WAIT_V(8); PG8_WAIT_L(0); PG8_BAR; PG8_MMA(0, 0, At, B0); PG8_MMA(0, 1, At, B1); PG8_BAR; PG8_SCHED;
;     ...
; #pragma unroll
;         for (int a = 0; a < 2; ++a)
; #pragma unroll
;             for (int b = 0; b < 2; ++b)
; #pragma unroll
;                 for (int m = 0; m < 4; ++m)
; #pragma unroll
;                     for (int n = 0; n < 2; ++n) acc[a][b][m][n] = (f32x4){0.f, 0.f, 0.f, 0.f};
;         cur = nxt; cA = nA; cB = nB; ++ui;
.LBB0_98:
	s_ashr_i32 s13, s12, 31
	s_lshl_b64 s[14:15], s[12:13], 19
	s_add_u32 s14, s27, s14
	s_addc_u32 s15, s34, s15
	s_and_b64 s[16:17], s[2:3], exec
	s_cselect_b32 s13, s15, s19
	s_cselect_b32 s45, s14, s18
	s_ashr_i32 s11, s10, 31
	s_lshl_b64 s[16:17], s[10:11], 19
	s_add_u32 s16, s24, s16
	s_addc_u32 s17, s25, s17
	s_and_b64 s[22:23], s[2:3], exec
	s_cselect_b32 s11, s17, s21
	s_cselect_b32 s46, s16, s20
	s_add_u32 s18, s18, 0x40080
	s_addc_u32 s19, s19, 0
	s_add_u32 s47, s20, 0x100
	v_mov_b32_e32 v4, 0
	s_addc_u32 s48, s21, 0
	s_mov_b32 s49, -2
	v_mov_b64_e32 v[4:5], 0
	v_mov_b64_e32 v[6:7], 0
	v_mov_b64_e32 v[8:9], 0
	v_mov_b64_e32 v[10:11], 0
	v_mov_b64_e32 v[12:13], 0
	v_mov_b64_e32 v[14:15], 0
	v_mov_b64_e32 v[16:17], 0
	v_mov_b64_e32 v[18:19], 0
	v_mov_b64_e32 v[20:21], 0
	v_mov_b64_e32 v[22:23], 0
	v_mov_b64_e32 v[24:25], 0
	v_mov_b64_e32 v[26:27], 0
	v_mov_b64_e32 v[28:29], 0
	v_mov_b64_e32 v[30:31], 0
	v_mov_b64_e32 v[32:33], 0
	v_mov_b64_e32 v[34:35], 0
	v_mov_b64_e32 v[36:37], 0
	v_mov_b64_e32 v[38:39], 0
	v_mov_b64_e32 v[40:41], 0
	v_mov_b64_e32 v[42:43], 0
	v_mov_b64_e32 v[44:45], 0
	v_mov_b64_e32 v[46:47], 0
	v_mov_b64_e32 v[48:49], 0
	v_mov_b64_e32 v[50:51], 0
	v_mov_b64_e32 v[52:53], 0
	v_mov_b64_e32 v[54:55], 0
	v_mov_b64_e32 v[56:57], 0
	v_mov_b64_e32 v[58:59], 0
	v_mov_b64_e32 v[60:61], 0
	v_mov_b64_e32 v[62:63], 0
	v_mov_b64_e32 v[64:65], 0
	v_mov_b64_e32 v[66:67], 0
	v_mov_b64_e32 v[68:69], 0
	v_mov_b64_e32 v[70:71], 0
	v_mov_b64_e32 v[72:73], 0
	v_mov_b64_e32 v[74:75], 0
	v_mov_b64_e32 v[76:77], 0
	v_mov_b64_e32 v[78:79], 0
	v_mov_b64_e32 v[80:81], 0
	v_mov_b64_e32 v[82:83], 0
	v_mov_b64_e32 v[84:85], 0
	v_mov_b64_e32 v[86:87], 0
	v_mov_b64_e32 v[88:89], 0
	v_mov_b64_e32 v[90:91], 0
	v_mov_b64_e32 v[92:93], 0
	v_mov_b64_e32 v[94:95], 0
	v_mov_b64_e32 v[96:97], 0
	v_mov_b64_e32 v[98:99], 0
	v_mov_b64_e32 v[100:101], 0
	v_mov_b64_e32 v[102:103], 0
	v_mov_b64_e32 v[104:105], 0
	v_mov_b64_e32 v[106:107], 0
	v_mov_b64_e32 v[108:109], 0
	v_mov_b64_e32 v[110:111], 0
	v_mov_b64_e32 v[112:113], 0
	v_mov_b64_e32 v[114:115], 0
	v_mov_b64_e32 v[128:129], 0
	v_mov_b64_e32 v[130:131], 0
	v_mov_b64_e32 v[136:137], 0
	v_mov_b64_e32 v[138:139], 0
	v_mov_b64_e32 v[140:141], 0
	v_mov_b64_e32 v[142:143], 0
	v_mov_b64_e32 v[144:145], 0
	v_mov_b64_e32 v[146:147], 0
	s_cmp_lt_u32 s92, 4
	s_cbranch_scc1 .Lprio_skip0
	s_setprio 1
.Lprio_skip0:
.LBB0_99:
	s_add_u32 s20, s18, 0xfffc0080
	s_addc_u32 s21, s19, -1
	s_add_i32 s50, 0, 0x10000
	s_cmp_eq_u32 s49, 12
	s_cselect_b32 s23, s13, s21
	s_cselect_b32 s22, s45, s20
	s_cselect_b32 s21, s11, s48
	s_cselect_b32 s20, s46, s47
	s_add_i32 s52, 0, 0x14000
	v_add_u32_e32 v132, s50, v153
	v_add_u32_e32 v148, s52, v153
	ds_read_b128 v[116:119], v132
	ds_read_b128 v[120:123], v132 offset:1024
	ds_read_b128 v[124:127], v132 offset:2048
	ds_read_b128 v[132:135], v132 offset:3072
	ds_read_b128 v[178:181], v148
	ds_read_b128 v[182:185], v148 offset:1024
	ds_read_b128 v[186:189], v148 offset:2048
	ds_read_b128 v[190:193], v148 offset:3072
	v_lshl_add_u64 v[148:149], s[18:19], 0, v[172:173]
	s_add_i32 m0, s36, 0xc000
	ds_read_b128 v[194:197], v176
	ds_read_b128 v[198:201], v176 offset:1024
	ds_read_b128 v[202:205], v176 offset:2048
	ds_read_b128 v[206:209], v176 offset:3072
	ds_read_b128 v[210:213], v176 offset:4096
	ds_read_b128 v[214:217], v176 offset:5120
	ds_read_b128 v[218:221], v176 offset:6144
	ds_read_b128 v[222:225], v176 offset:7168
	global_load_lds_dwordx4 v[148:149], off
	v_lshl_add_u64 v[148:149], s[18:19], 0, v[174:175]
	s_add_i32 m0, s36, 0xe000
	s_nop 0
	global_load_lds_dwordx4 v[148:149], off
	s_waitcnt vmcnt(8)
	s_waitcnt lgkmcnt(0)
	s_barrier
	s_waitcnt lgkmcnt(0)
	v_mfma_f32_16x16x32_bf16 v[144:147], v[116:119], v[194:197], v[144:147]
	v_mfma_f32_16x16x32_bf16 v[140:143], v[124:127], v[194:197], v[140:143]
	v_mfma_f32_16x16x32_bf16 v[112:115], v[116:119], v[202:205], v[112:115]
	v_mfma_f32_16x16x32_bf16 v[108:111], v[124:127], v[202:205], v[108:111]
	v_mfma_f32_16x16x32_bf16 v[96:99], v[116:119], v[210:213], v[96:99]
	v_mfma_f32_16x16x32_bf16 v[92:95], v[124:127], v[210:213], v[92:95]
	v_mfma_f32_16x16x32_bf16 v[80:83], v[116:119], v[218:221], v[80:83]
	v_mfma_f32_16x16x32_bf16 v[76:79], v[124:127], v[218:221], v[76:79]
	v_mfma_f32_16x16x32_bf16 v[144:147], v[120:123], v[198:201], v[144:147]
	v_mfma_f32_16x16x32_bf16 v[140:143], v[132:135], v[198:201], v[140:143]
	v_mfma_f32_16x16x32_bf16 v[112:115], v[120:123], v[206:209], v[112:115]
	v_mfma_f32_16x16x32_bf16 v[108:111], v[132:135], v[206:209], v[108:111]
	v_mfma_f32_16x16x32_bf16 v[96:99], v[120:123], v[214:217], v[96:99]
	v_mfma_f32_16x16x32_bf16 v[92:95], v[132:135], v[214:217], v[92:95]
	v_mfma_f32_16x16x32_bf16 v[80:83], v[120:123], v[222:225], v[80:83]
	v_mfma_f32_16x16x32_bf16 v[76:79], v[132:135], v[222:225], v[76:79]
	v_mfma_f32_16x16x32_bf16 v[136:139], v[178:181], v[194:197], v[136:139]
	v_mfma_f32_16x16x32_bf16 v[128:131], v[186:189], v[194:197], v[128:131]
	v_mfma_f32_16x16x32_bf16 v[104:107], v[178:181], v[202:205], v[104:107]
	v_mfma_f32_16x16x32_bf16 v[100:103], v[186:189], v[202:205], v[100:103]
	v_mfma_f32_16x16x32_bf16 v[88:91], v[178:181], v[210:213], v[88:91]
	v_mfma_f32_16x16x32_bf16 v[84:87], v[186:189], v[210:213], v[84:87]
	v_mfma_f32_16x16x32_bf16 v[72:75], v[178:181], v[218:221], v[72:75]
	v_mfma_f32_16x16x32_bf16 v[68:71], v[186:189], v[218:221], v[68:71]
	v_mfma_f32_16x16x32_bf16 v[136:139], v[182:185], v[198:201], v[136:139]
	v_mfma_f32_16x16x32_bf16 v[128:131], v[190:193], v[198:201], v[128:131]
	v_mfma_f32_16x16x32_bf16 v[104:107], v[182:185], v[206:209], v[104:107]
	v_mfma_f32_16x16x32_bf16 v[100:103], v[190:193], v[206:209], v[100:103]
	v_mfma_f32_16x16x32_bf16 v[88:91], v[182:185], v[214:217], v[88:91]
	v_mfma_f32_16x16x32_bf16 v[84:87], v[190:193], v[214:217], v[84:87]
	v_mfma_f32_16x16x32_bf16 v[72:75], v[182:185], v[222:225], v[72:75]
	v_mfma_f32_16x16x32_bf16 v[68:71], v[190:193], v[222:225], v[68:71]
	s_barrier
; #define PG8_STAGE(bufoff, gbase, voff) do { _Pragma("unroll") for (int _i = 0; _i < 2; ++_i) \
;         __builtin_amdgcn_global_load_lds((const unsigned*)((const char*)(gbase) + (voff)[_i]), (PG8_LAS unsigned*)(lds + (bufoff) + ldsw + _i * 8192), 16, 0, 0); } while (0)
; #define PG8_LDA(dst, b, h) do { _Pragma("unroll") for (int m = 0; m < 4; ++m) _Pragma("unroll") for (int k = 0; k < 2; ++k) dst[m][k] = *(const PG8_LAS bf16x8*)(lds + PG8_SA(b, h) + aoff + m * 2048 + k * 1024); } while (0)
; #define PG8_LDB(dst, b, h) do { _Pragma("unroll") for (int n = 0; n < 2; ++n) _Pragma("unroll") for (int k = 0; k < 2; ++k) dst[n][k] = *(const PG8_LAS bf16x8*)(lds + PG8_SB(b, h) + boff + n * 2048 + k * 1024); } while (0)
; #define PG8_MMA(ai, bj, At, Bt) do { __builtin_amdgcn_s_setprio(1); _Pragma("unroll") for (int m = 0; m < 4; ++m) _Pragma("unroll") for (int n = 0; n < 2; ++n) _Pragma("unroll") for (int k = 0; k < 2; ++k) \
;         acc[ai][bj][m][n] = __builtin_amdgcn_mfma_f32_16x16x32_bf16(Bt[n][k], At[m][k], acc[ai][bj][m][n], 0, 0, 0); __builtin_amdgcn_s_setprio(0); } while (0)
; #define PG8_WAIT_V(n) asm volatile("s_waitcnt vmcnt(" #n ")" ::: "memory")
; #define PG8_WAIT_L(n) asm volatile("s_waitcnt lgkmcnt(" #n ")" ::: "memory")
; #define PG8_BAR __builtin_amdgcn_s_barrier()
; #define PG8_SCHED __builtin_amdgcn_sched_barrier(0)
; template <class Epi, class Sched, bool ALIGN_EPI = false, bool SP2 = false>
; __device__ __forceinline__ void gemm_phase(PG8_LAS unsigned char* lds, const Gemm g, const Sched& S, const Epi& E, const int tid) {
;     ...
;             if constexpr (SP2) {
;             PG8_LDB(B0, 0, 0); PG8_LDB(B1, 0, 1); PG8_SCHED; PG8_LDA(At, 0, 0); PG8_STAGE(PG8_SA(1, 1), a1 + hstep, voffA);
;             PG8_WAIT_V(8); PG8_WAIT_L(0); PG8_BAR; PG8_MMA(0, 0, At, B0); PG8_MMA(0, 1, At, B1); PG8_BAR; PG8_SCHED;
;             PG8_LDA(At, 0, 1); PG8_STAGE(PG8_SB(0, 0), b2, voffB); PG8_STAGE(PG8_SB(0, 1), b2 + hstep, voffB); PG8_STAGE(PG8_SA(0, 0), a2, voffA);
;             PG8_WAIT_V(8); PG8_WAIT_L(0); PG8_BAR; PG8_MMA(1, 0, At, B0); PG8_MMA(1, 1, At, B1); PG8_BAR; PG8_SCHED;
;             PG8_LDB(B0, 1, 0); PG8_LDB(B1, 1, 1); PG8_SCHED; PG8_LDA(At, 1, 0); PG8_STAGE(PG8_SA(0, 1), a2 + hstep, voffA);
;             PG8_WAIT_V(8); PG8_WAIT_L(0); PG8_BAR; PG8_MMA(0, 0, At, B0); PG8_MMA(0, 1, At, B1); PG8_BAR; PG8_SCHED;
	s_add_i32 s50, s50, s26
	v_lshl_add_u64 v[148:149], s[20:21], 0, v[168:169]
	s_mov_b32 m0, s50
	ds_read_b128 v[194:197], v176 offset:16384
	ds_read_b128 v[198:201], v176 offset:17408
	ds_read_b128 v[202:205], v176 offset:18432
	ds_read_b128 v[206:209], v176 offset:19456
	ds_read_b128 v[210:213], v176 offset:20480
	ds_read_b128 v[214:217], v176 offset:21504
	ds_read_b128 v[218:221], v176 offset:22528
	ds_read_b128 v[222:225], v176 offset:23552
	global_load_lds_dwordx4 v[148:149], off
	s_add_i32 m0, s50, 0x2000
	s_add_u32 s50, s20, 0x40000
	v_lshl_add_u64 v[150:151], s[20:21], 0, v[0:1]
	s_addc_u32 s51, s21, 0
	s_add_i32 s52, s52, s26
	global_load_lds_dwordx4 v[150:151], off
	v_lshl_add_u64 v[226:227], s[50:51], 0, v[168:169]
	s_mov_b32 m0, s52
	v_lshl_add_u64 v[238:239], s[22:23], 0, v[166:167]
	global_load_lds_dwordx4 v[226:227], off
	v_lshl_add_u64 v[226:227], s[50:51], 0, v[0:1]
	s_add_i32 m0, s52, 0x2000
	s_nop 0
	global_load_lds_dwordx4 v[226:227], off
	v_lshl_add_u64 v[226:227], s[22:23], 0, v[170:171]
	s_mov_b32 m0, s36
	s_nop 0
	global_load_lds_dwordx4 v[226:227], off
	s_mov_b32 m0, s37
	s_nop 0
	global_load_lds_dwordx4 v[238:239], off
	s_waitcnt vmcnt(8)
	s_waitcnt lgkmcnt(0)
	s_barrier
	s_waitcnt lgkmcnt(0)
	v_mfma_f32_16x16x32_bf16 v[64:67], v[116:119], v[194:197], v[64:67]
	v_mfma_f32_16x16x32_bf16 v[60:63], v[124:127], v[194:197], v[60:63]
	v_mfma_f32_16x16x32_bf16 v[56:59], v[116:119], v[202:205], v[56:59]
	v_mfma_f32_16x16x32_bf16 v[48:51], v[124:127], v[202:205], v[48:51]
	v_mfma_f32_16x16x32_bf16 v[40:43], v[116:119], v[210:213], v[40:43]
	v_mfma_f32_16x16x32_bf16 v[32:35], v[124:127], v[210:213], v[32:35]
	v_mfma_f32_16x16x32_bf16 v[24:27], v[116:119], v[218:221], v[24:27]
	v_mfma_f32_16x16x32_bf16 v[16:19], v[124:127], v[218:221], v[16:19]
	v_mfma_f32_16x16x32_bf16 v[64:67], v[120:123], v[198:201], v[64:67]
	v_mfma_f32_16x16x32_bf16 v[60:63], v[132:135], v[198:201], v[60:63]
	v_mfma_f32_16x16x32_bf16 v[56:59], v[120:123], v[206:209], v[56:59]
	v_mfma_f32_16x16x32_bf16 v[48:51], v[132:135], v[206:209], v[48:51]
	v_mfma_f32_16x16x32_bf16 v[40:43], v[120:123], v[214:217], v[40:43]
	v_mfma_f32_16x16x32_bf16 v[32:35], v[132:135], v[214:217], v[32:35]
	v_mfma_f32_16x16x32_bf16 v[24:27], v[120:123], v[222:225], v[24:27]
	v_mfma_f32_16x16x32_bf16 v[16:19], v[132:135], v[222:225], v[16:19]
	v_mfma_f32_16x16x32_bf16 v[52:55], v[178:181], v[194:197], v[52:55]
	v_mfma_f32_16x16x32_bf16 v[44:47], v[186:189], v[194:197], v[44:47]
	v_mfma_f32_16x16x32_bf16 v[36:39], v[178:181], v[202:205], v[36:39]
	v_mfma_f32_16x16x32_bf16 v[28:31], v[186:189], v[202:205], v[28:31]
	v_mfma_f32_16x16x32_bf16 v[20:23], v[178:181], v[210:213], v[20:23]
	v_mfma_f32_16x16x32_bf16 v[12:15], v[186:189], v[210:213], v[12:15]
	v_mfma_f32_16x16x32_bf16 v[8:11], v[178:181], v[218:221], v[8:11]
	v_mfma_f32_16x16x32_bf16 v[4:7], v[186:189], v[218:221], v[4:7]
	v_mfma_f32_16x16x32_bf16 v[52:55], v[182:185], v[198:201], v[52:55]
	v_mfma_f32_16x16x32_bf16 v[44:47], v[190:193], v[198:201], v[44:47]
	v_mfma_f32_16x16x32_bf16 v[36:39], v[182:185], v[206:209], v[36:39]
	v_mfma_f32_16x16x32_bf16 v[28:31], v[190:193], v[206:209], v[28:31]
	v_mfma_f32_16x16x32_bf16 v[20:23], v[182:185], v[214:217], v[20:23]
	v_mfma_f32_16x16x32_bf16 v[12:15], v[190:193], v[214:217], v[12:15]
	v_mfma_f32_16x16x32_bf16 v[8:11], v[182:185], v[222:225], v[8:11]
	v_mfma_f32_16x16x32_bf16 v[4:7], v[190:193], v[222:225], v[4:7]
	s_barrier
	s_add_i32 s50, 0, 0x18000
	s_add_i32 s51, 0, 0x1c000
	v_add_u32_e32 v132, s50, v153
	v_add_u32_e32 v177, s51, v153
	ds_read_b128 v[116:119], v132
	ds_read_b128 v[120:123], v132 offset:1024
	ds_read_b128 v[124:127], v132 offset:2048
	ds_read_b128 v[132:135], v132 offset:3072
	ds_read_b128 v[178:181], v177
	ds_read_b128 v[182:185], v177 offset:1024
	ds_read_b128 v[186:189], v177 offset:2048
	ds_read_b128 v[190:193], v177 offset:3072
	s_add_u32 s22, s22, 0x40000
	s_addc_u32 s23, s23, 0
	s_mov_b32 m0, s38
	v_lshl_add_u64 v[240:241], s[22:23], 0, v[170:171]
	ds_read_b128 v[194:197], v176 offset:32768
	ds_read_b128 v[198:201], v176 offset:33792
	ds_read_b128 v[202:205], v176 offset:34816
	ds_read_b128 v[206:209], v176 offset:35840
	ds_read_b128 v[210:213], v176 offset:36864
	ds_read_b128 v[214:217], v176 offset:37888
	ds_read_b128 v[218:221], v176 offset:38912
	ds_read_b128 v[222:225], v176 offset:39936
	global_load_lds_dwordx4 v[240:241], off
	v_lshl_add_u64 v[240:241], s[22:23], 0, v[166:167]
	s_mov_b32 m0, s39
	s_nop 0
	global_load_lds_dwordx4 v[240:241], off
	s_waitcnt vmcnt(8)
	s_waitcnt lgkmcnt(0)
	s_barrier
; #define PG8_STAGE(bufoff, gbase, voff) do { _Pragma("unroll") for (int _i = 0; _i < 2; ++_i) \
;         __builtin_amdgcn_global_load_lds((const unsigned*)((const char*)(gbase) + (voff)[_i]), (PG8_LAS unsigned*)(lds + (bufoff) + ldsw + _i * 8192), 16, 0, 0); } while (0)
; #define PG8_LDA(dst, b, h) do { _Pragma("unroll") for (int m = 0; m < 4; ++m) _Pragma("unroll") for (int k = 0; k < 2; ++k) dst[m][k] = *(const PG8_LAS bf16x8*)(lds + PG8_SA(b, h) + aoff + m * 2048 + k * 1024); } while (0)
; #define PG8_LDB(dst, b, h) do { _Pragma("unroll") for (int n = 0; n < 2; ++n) _Pragma("unroll") for (int k = 0; k < 2; ++k) dst[n][k] = *(const PG8_LAS bf16x8*)(lds + PG8_SB(b, h) + boff + n * 2048 + k * 1024); } while (0)
; #define PG8_MMA(ai, bj, At, Bt) do { __builtin_amdgcn_s_setprio(1); _Pragma("unroll") for (int m = 0; m < 4; ++m) _Pragma("unroll") for (int n = 0; n < 2; ++n) _Pragma("unroll") for (int k = 0; k < 2; ++k) \
;         acc[ai][bj][m][n] = __builtin_amdgcn_mfma_f32_16x16x32_bf16(Bt[n][k], At[m][k], acc[ai][bj][m][n], 0, 0, 0); __builtin_amdgcn_s_setprio(0); } while (0)
; #define PG8_WAIT_V(n) asm volatile("s_waitcnt vmcnt(" #n ")" ::: "memory")
; #define PG8_WAIT_L(n) asm volatile("s_waitcnt lgkmcnt(" #n ")" ::: "memory")
; template <class Epi, class Sched, bool ALIGN_EPI = false, bool SP2 = false>
; __device__ __forceinline__ void gemm_phase(PG8_LAS unsigned char* lds, const Gemm g, const Sched& S, const Epi& E, const int tid) {
;     ...
;             PG8_WAIT_V(8); PG8_WAIT_L(0); PG8_BAR; PG8_MMA(0, 0, At, B0); PG8_MMA(0, 1, At, B1); PG8_BAR; PG8_SCHED;
;             PG8_LDA(At, 0, 1); PG8_STAGE(PG8_SB(0, 0), b2, voffB); PG8_STAGE(PG8_SB(0, 1), b2 + hstep, voffB); PG8_STAGE(PG8_SA(0, 0), a2, voffA);
;             PG8_WAIT_V(8); PG8_WAIT_L(0); PG8_BAR; PG8_MMA(1, 0, At, B0); PG8_MMA(1, 1, At, B1); PG8_BAR; PG8_SCHED;
;             PG8_LDB(B0, 1, 0); PG8_LDB(B1, 1, 1); PG8_SCHED; PG8_LDA(At, 1, 0); PG8_STAGE(PG8_SA(0, 1), a2 + hstep, voffA);
;             PG8_WAIT_V(8); PG8_WAIT_L(0); PG8_BAR; PG8_MMA(0, 0, At, B0); PG8_MMA(0, 1, At, B1); PG8_BAR; PG8_SCHED;
;             PG8_LDA(At, 1, 1); PG8_STAGE(PG8_SB(1, 0), b3, voffB); PG8_STAGE(PG8_SB(1, 1), b3 + hstep, voffB); PG8_STAGE(PG8_SA(1, 0), a3, voffA);
;             PG8_WAIT_V(8); PG8_WAIT_L(0); PG8_BAR; PG8_MMA(1, 0, At, B0); PG8_MMA(1, 1, At, B1); PG8_BAR; PG8_SCHED;
	s_waitcnt lgkmcnt(0)
	v_mfma_f32_16x16x32_bf16 v[144:147], v[116:119], v[194:197], v[144:147]
	v_mfma_f32_16x16x32_bf16 v[140:143], v[124:127], v[194:197], v[140:143]
	v_mfma_f32_16x16x32_bf16 v[112:115], v[116:119], v[202:205], v[112:115]
	v_mfma_f32_16x16x32_bf16 v[108:111], v[124:127], v[202:205], v[108:111]
	v_mfma_f32_16x16x32_bf16 v[96:99], v[116:119], v[210:213], v[96:99]
	v_mfma_f32_16x16x32_bf16 v[92:95], v[124:127], v[210:213], v[92:95]
	v_mfma_f32_16x16x32_bf16 v[80:83], v[116:119], v[218:221], v[80:83]
	v_mfma_f32_16x16x32_bf16 v[76:79], v[124:127], v[218:221], v[76:79]
	v_mfma_f32_16x16x32_bf16 v[144:147], v[120:123], v[198:201], v[144:147]
	v_mfma_f32_16x16x32_bf16 v[140:143], v[132:135], v[198:201], v[140:143]
	v_mfma_f32_16x16x32_bf16 v[112:115], v[120:123], v[206:209], v[112:115]
	v_mfma_f32_16x16x32_bf16 v[108:111], v[132:135], v[206:209], v[108:111]
	v_mfma_f32_16x16x32_bf16 v[96:99], v[120:123], v[214:217], v[96:99]
	v_mfma_f32_16x16x32_bf16 v[92:95], v[132:135], v[214:217], v[92:95]
	v_mfma_f32_16x16x32_bf16 v[80:83], v[120:123], v[222:225], v[80:83]
	v_mfma_f32_16x16x32_bf16 v[76:79], v[132:135], v[222:225], v[76:79]
	v_mfma_f32_16x16x32_bf16 v[136:139], v[178:181], v[194:197], v[136:139]
	v_mfma_f32_16x16x32_bf16 v[128:131], v[186:189], v[194:197], v[128:131]
	v_mfma_f32_16x16x32_bf16 v[104:107], v[178:181], v[202:205], v[104:107]
	v_mfma_f32_16x16x32_bf16 v[100:103], v[186:189], v[202:205], v[100:103]
	v_mfma_f32_16x16x32_bf16 v[88:91], v[178:181], v[210:213], v[88:91]
	v_mfma_f32_16x16x32_bf16 v[84:87], v[186:189], v[210:213], v[84:87]
	v_mfma_f32_16x16x32_bf16 v[72:75], v[178:181], v[218:221], v[72:75]
	v_mfma_f32_16x16x32_bf16 v[68:71], v[186:189], v[218:221], v[68:71]
	v_mfma_f32_16x16x32_bf16 v[136:139], v[182:185], v[198:201], v[136:139]
	v_mfma_f32_16x16x32_bf16 v[128:131], v[190:193], v[198:201], v[128:131]
	v_mfma_f32_16x16x32_bf16 v[104:107], v[182:185], v[206:209], v[104:107]
	v_mfma_f32_16x16x32_bf16 v[100:103], v[190:193], v[206:209], v[100:103]
	v_mfma_f32_16x16x32_bf16 v[88:91], v[182:185], v[214:217], v[88:91]
	v_mfma_f32_16x16x32_bf16 v[84:87], v[190:193], v[214:217], v[84:87]
	v_mfma_f32_16x16x32_bf16 v[72:75], v[182:185], v[222:225], v[72:75]
	v_mfma_f32_16x16x32_bf16 v[68:71], v[190:193], v[222:225], v[68:71]
	s_barrier
	s_add_i32 s22, s50, s26
	v_lshl_add_u64 v[148:149], v[148:149], 0, s[0:1]
	s_mov_b32 m0, s22
	ds_read_b128 v[194:197], v176 offset:49152
	ds_read_b128 v[198:201], v176 offset:50176
	ds_read_b128 v[202:205], v176 offset:51200
	ds_read_b128 v[206:209], v176 offset:52224
	ds_read_b128 v[210:213], v176 offset:53248
	ds_read_b128 v[214:217], v176 offset:54272
	ds_read_b128 v[218:221], v176 offset:55296
	ds_read_b128 v[222:225], v176 offset:56320
	global_load_lds_dwordx4 v[148:149], off
	s_add_i32 m0, s22, 0x2000
	s_add_u32 s20, s20, 0x40080
	v_lshl_add_u64 v[148:149], v[150:151], 0, s[0:1]
	s_addc_u32 s21, s21, 0
	s_add_i32 s22, s51, s26
	global_load_lds_dwordx4 v[148:149], off
	v_lshl_add_u64 v[148:149], s[20:21], 0, v[168:169]
	s_mov_b32 m0, s22
	s_nop 0
	global_load_lds_dwordx4 v[148:149], off
	v_lshl_add_u64 v[148:149], s[20:21], 0, v[0:1]
	s_add_i32 m0, s22, 0x2000
	s_nop 0
	global_load_lds_dwordx4 v[148:149], off
	v_lshl_add_u64 v[148:149], v[226:227], 0, s[0:1]
	s_mov_b32 m0, s40
	s_nop 0
	global_load_lds_dwordx4 v[148:149], off
	v_lshl_add_u64 v[148:149], v[238:239], 0, s[0:1]
	s_mov_b32 m0, s41
	s_nop 0
	global_load_lds_dwordx4 v[148:149], off
	s_waitcnt vmcnt(8)
	s_waitcnt lgkmcnt(0)
	s_barrier
	s_waitcnt lgkmcnt(0)
	v_mfma_f32_16x16x32_bf16 v[64:67], v[116:119], v[194:197], v[64:67]
	v_mfma_f32_16x16x32_bf16 v[60:63], v[124:127], v[194:197], v[60:63]
	v_mfma_f32_16x16x32_bf16 v[56:59], v[116:119], v[202:205], v[56:59]
	v_mfma_f32_16x16x32_bf16 v[48:51], v[124:127], v[202:205], v[48:51]
	v_mfma_f32_16x16x32_bf16 v[40:43], v[116:119], v[210:213], v[40:43]
	v_mfma_f32_16x16x32_bf16 v[32:35], v[124:127], v[210:213], v[32:35]
	v_mfma_f32_16x16x32_bf16 v[24:27], v[116:119], v[218:221], v[24:27]
	v_mfma_f32_16x16x32_bf16 v[16:19], v[124:127], v[218:221], v[16:19]
	v_mfma_f32_16x16x32_bf16 v[64:67], v[120:123], v[198:201], v[64:67]
	v_mfma_f32_16x16x32_bf16 v[60:63], v[132:135], v[198:201], v[60:63]
	v_mfma_f32_16x16x32_bf16 v[56:59], v[120:123], v[206:209], v[56:59]
	v_mfma_f32_16x16x32_bf16 v[48:51], v[132:135], v[206:209], v[48:51]
	v_mfma_f32_16x16x32_bf16 v[40:43], v[120:123], v[214:217], v[40:43]
	v_mfma_f32_16x16x32_bf16 v[32:35], v[132:135], v[214:217], v[32:35]
	v_mfma_f32_16x16x32_bf16 v[24:27], v[120:123], v[222:225], v[24:27]
	v_mfma_f32_16x16x32_bf16 v[16:19], v[132:135], v[222:225], v[16:19]
	v_mfma_f32_16x16x32_bf16 v[52:55], v[178:181], v[194:197], v[52:55]
	v_mfma_f32_16x16x32_bf16 v[44:47], v[186:189], v[194:197], v[44:47]
	v_mfma_f32_16x16x32_bf16 v[36:39], v[178:181], v[202:205], v[36:39]
	v_mfma_f32_16x16x32_bf16 v[28:31], v[186:189], v[202:205], v[28:31]
	v_mfma_f32_16x16x32_bf16 v[20:23], v[178:181], v[210:213], v[20:23]
	v_mfma_f32_16x16x32_bf16 v[12:15], v[186:189], v[210:213], v[12:15]
	v_mfma_f32_16x16x32_bf16 v[8:11], v[178:181], v[218:221], v[8:11]
	v_mfma_f32_16x16x32_bf16 v[4:7], v[186:189], v[218:221], v[4:7]
	v_mfma_f32_16x16x32_bf16 v[52:55], v[182:185], v[198:201], v[52:55]
	v_mfma_f32_16x16x32_bf16 v[44:47], v[190:193], v[198:201], v[44:47]
	v_mfma_f32_16x16x32_bf16 v[36:39], v[182:185], v[206:209], v[36:39]
	v_mfma_f32_16x16x32_bf16 v[28:31], v[190:193], v[206:209], v[28:31]
	v_mfma_f32_16x16x32_bf16 v[20:23], v[182:185], v[214:217], v[20:23]
	v_mfma_f32_16x16x32_bf16 v[12:15], v[190:193], v[214:217], v[12:15]
	v_mfma_f32_16x16x32_bf16 v[8:11], v[182:185], v[222:225], v[8:11]
	v_mfma_f32_16x16x32_bf16 v[4:7], v[190:193], v[222:225], v[4:7]
	s_barrier
	s_add_i32 s49, s49, 2
	s_add_u32 s18, s18, 0x100
	s_addc_u32 s19, s19, 0
	s_add_u32 s47, s47, 0x100
	s_addc_u32 s48, s48, 0
	s_cmp_gt_u32 s49, 13
	s_cbranch_scc0 .LBB0_99
	s_setprio 0
	s_and_b64 vcc, exec, s[8:9]
	s_cbranch_vccz .LBB0_102
	s_barrier

; template <class Epi, class Sched, bool ALIGN_EPI = false, bool SP2 = false>
; __device__ __forceinline__ void gemm_phase(PG8_LAS unsigned char* lds, const Gemm g, const Sched& S, const Epi& E, const int tid) {
;     ...
;         const bool has_next = S.next(ui + 1, nxt);
;         const char* nA = has_next ? (const char*)g.A + (size_t)nxt.pm * tstep : cA; const char* nB = has_next ? (const char*)g.Bt + (size_t)nxt.pn * tstep : cB;
;     ...
; #pragma unroll
;         for (int a = 0; a < 2; ++a)
; #pragma unroll
;             for (int b = 0; b < 2; ++b)
; #pragma unroll
;                 for (int m = 0; m < 4; ++m)
; #pragma unroll
;                     for (int n = 0; n < 2; ++n) acc[a][b][m][n] = (f32x4){0.f, 0.f, 0.f, 0.f};
;         cur = nxt; cA = nA; cB = nB; ++ui;
.LBB0_292:
	s_ashr_i32 s17, s16, 31
	s_lshl_b64 s[18:19], s[16:17], 19
	s_add_u32 s18, s34, s18
	s_addc_u32 s19, s40, s19
	s_and_b64 s[20:21], s[4:5], exec
	s_cselect_b32 s17, s19, s3
	s_cselect_b32 s23, s18, s2
	s_ashr_i32 s15, s14, 31
	s_lshl_b64 s[20:21], s[14:15], 19
	s_add_u32 s20, s41, s20
	s_addc_u32 s21, s42, s21
	s_and_b64 s[36:37], s[4:5], exec
	s_cselect_b32 s15, s21, s27
	s_cselect_b32 s51, s20, s26
	s_add_u32 s2, s2, 0x40080
	s_addc_u32 s3, s3, 0
	s_add_u32 s52, s26, 0x100
	v_mov_b32_e32 v12, 0
	s_addc_u32 s53, s27, 0
	s_mov_b32 s54, -2
	v_mov_b64_e32 v[4:5], 0
	v_mov_b64_e32 v[6:7], 0
	v_mov_b64_e32 v[8:9], 0
	v_mov_b64_e32 v[10:11], 0
	v_mov_b64_e32 v[12:13], 0
	v_mov_b64_e32 v[14:15], 0
	v_mov_b64_e32 v[16:17], 0
	v_mov_b64_e32 v[18:19], 0
	v_mov_b64_e32 v[20:21], 0
	v_mov_b64_e32 v[22:23], 0
	v_mov_b64_e32 v[24:25], 0
	v_mov_b64_e32 v[26:27], 0
	v_mov_b64_e32 v[28:29], 0
	v_mov_b64_e32 v[30:31], 0
	v_mov_b64_e32 v[32:33], 0
	v_mov_b64_e32 v[34:35], 0
	v_mov_b64_e32 v[36:37], 0
	v_mov_b64_e32 v[38:39], 0
	v_mov_b64_e32 v[40:41], 0
	v_mov_b64_e32 v[42:43], 0
	v_mov_b64_e32 v[44:45], 0
	v_mov_b64_e32 v[46:47], 0
	v_mov_b64_e32 v[48:49], 0
	v_mov_b64_e32 v[50:51], 0
	v_mov_b64_e32 v[52:53], 0
	v_mov_b64_e32 v[54:55], 0
	v_mov_b64_e32 v[56:57], 0
	v_mov_b64_e32 v[58:59], 0
	v_mov_b64_e32 v[60:61], 0
	v_mov_b64_e32 v[62:63], 0
	v_mov_b64_e32 v[64:65], 0
	v_mov_b64_e32 v[66:67], 0
	v_mov_b64_e32 v[68:69], 0
	v_mov_b64_e32 v[70:71], 0
	v_mov_b64_e32 v[72:73], 0
	v_mov_b64_e32 v[74:75], 0
	v_mov_b64_e32 v[76:77], 0
	v_mov_b64_e32 v[78:79], 0
	v_mov_b64_e32 v[80:81], 0
	v_mov_b64_e32 v[82:83], 0
	v_mov_b64_e32 v[84:85], 0
	v_mov_b64_e32 v[86:87], 0
	v_mov_b64_e32 v[88:89], 0
	v_mov_b64_e32 v[90:91], 0
	v_mov_b64_e32 v[92:93], 0
	v_mov_b64_e32 v[94:95], 0
	v_mov_b64_e32 v[96:97], 0
	v_mov_b64_e32 v[98:99], 0
	v_mov_b64_e32 v[100:101], 0
	v_mov_b64_e32 v[102:103], 0
	v_mov_b64_e32 v[104:105], 0
	v_mov_b64_e32 v[106:107], 0
	v_mov_b64_e32 v[108:109], 0
	v_mov_b64_e32 v[110:111], 0
	v_mov_b64_e32 v[112:113], 0
	v_mov_b64_e32 v[114:115], 0
	v_mov_b64_e32 v[116:117], 0
	v_mov_b64_e32 v[118:119], 0
	v_mov_b64_e32 v[120:121], 0
	v_mov_b64_e32 v[122:123], 0
	v_mov_b64_e32 v[124:125], 0
	v_mov_b64_e32 v[126:127], 0
	v_mov_b64_e32 v[128:129], 0
	v_mov_b64_e32 v[130:131], 0
	s_cmp_lt_u32 s92, 4
	s_cbranch_scc1 .Lprio_skip1
	s_setprio 1
.Lprio_skip1:
.LBB0_293:
	s_add_u32 s26, s2, 0xfffc0080
	s_addc_u32 s27, s3, -1
	s_add_i32 s55, 0, 0x10000
	s_cmp_eq_u32 s54, 12
	s_cselect_b32 s37, s17, s27
	s_cselect_b32 s36, s23, s26
	v_add_u32_e32 v146, s55, v165
	s_cselect_b32 s27, s15, s53
	s_cselect_b32 s26, s51, s52
	s_add_i32 s58, 0, 0x14000
	ds_read_b128 v[166:169], v146
	ds_read_b128 v[172:175], v146 offset:1024
	ds_read_b128 v[176:179], v146 offset:2048
	ds_read_b128 v[180:183], v146 offset:3072
	v_add_u32_e32 v146, s58, v165
	ds_read_b128 v[184:187], v146
	ds_read_b128 v[188:191], v146 offset:1024
	ds_read_b128 v[192:195], v146 offset:2048
	ds_read_b128 v[196:199], v146 offset:3072
	v_lshl_add_u64 v[146:147], s[2:3], 0, v[142:143]
	s_add_i32 m0, s25, 0xc000
	ds_read_b128 v[200:203], v171
	ds_read_b128 v[204:207], v171 offset:1024
	ds_read_b128 v[208:211], v171 offset:2048
	ds_read_b128 v[212:215], v171 offset:3072
	ds_read_b128 v[216:219], v171 offset:4096
	ds_read_b128 v[220:223], v171 offset:5120
	ds_read_b128 v[224:227], v171 offset:6144
	ds_read_b128 v[238:241], v171 offset:7168
	global_load_lds_dwordx4 v[146:147], off
	v_lshl_add_u64 v[146:147], s[2:3], 0, v[144:145]
	s_add_i32 m0, s25, 0xe000
	s_nop 0
	global_load_lds_dwordx4 v[146:147], off
	s_waitcnt vmcnt(8)
	s_waitcnt lgkmcnt(0)
	s_barrier
	s_waitcnt lgkmcnt(0)
	v_mfma_f32_16x16x32_bf16 v[72:75], v[166:169], v[200:203], v[72:75]
	v_mfma_f32_16x16x32_bf16 v[68:71], v[176:179], v[200:203], v[68:71]
	v_mfma_f32_16x16x32_bf16 v[64:67], v[166:169], v[208:211], v[64:67]
	v_mfma_f32_16x16x32_bf16 v[60:63], v[176:179], v[208:211], v[60:63]
	v_mfma_f32_16x16x32_bf16 v[56:59], v[166:169], v[216:219], v[56:59]
	v_mfma_f32_16x16x32_bf16 v[52:55], v[176:179], v[216:219], v[52:55]
	v_mfma_f32_16x16x32_bf16 v[48:51], v[166:169], v[224:227], v[48:51]
	v_mfma_f32_16x16x32_bf16 v[44:47], v[176:179], v[224:227], v[44:47]
	v_mfma_f32_16x16x32_bf16 v[72:75], v[172:175], v[204:207], v[72:75]
	v_mfma_f32_16x16x32_bf16 v[68:71], v[180:183], v[204:207], v[68:71]
	v_mfma_f32_16x16x32_bf16 v[64:67], v[172:175], v[212:215], v[64:67]
	v_mfma_f32_16x16x32_bf16 v[60:63], v[180:183], v[212:215], v[60:63]
	v_mfma_f32_16x16x32_bf16 v[56:59], v[172:175], v[220:223], v[56:59]
	v_mfma_f32_16x16x32_bf16 v[52:55], v[180:183], v[220:223], v[52:55]
	v_mfma_f32_16x16x32_bf16 v[48:51], v[172:175], v[238:241], v[48:51]
	v_mfma_f32_16x16x32_bf16 v[44:47], v[180:183], v[238:241], v[44:47]
	v_mfma_f32_16x16x32_bf16 v[128:131], v[184:187], v[200:203], v[128:131]
	v_mfma_f32_16x16x32_bf16 v[124:127], v[192:195], v[200:203], v[124:127]
	v_mfma_f32_16x16x32_bf16 v[120:123], v[184:187], v[208:211], v[120:123]
	v_mfma_f32_16x16x32_bf16 v[116:119], v[192:195], v[208:211], v[116:119]
	v_mfma_f32_16x16x32_bf16 v[112:115], v[184:187], v[216:219], v[112:115]
	v_mfma_f32_16x16x32_bf16 v[108:111], v[192:195], v[216:219], v[108:111]
	v_mfma_f32_16x16x32_bf16 v[104:107], v[184:187], v[224:227], v[104:107]
	v_mfma_f32_16x16x32_bf16 v[100:103], v[192:195], v[224:227], v[100:103]
	v_mfma_f32_16x16x32_bf16 v[128:131], v[188:191], v[204:207], v[128:131]
	v_mfma_f32_16x16x32_bf16 v[124:127], v[196:199], v[204:207], v[124:127]
	v_mfma_f32_16x16x32_bf16 v[120:123], v[188:191], v[212:215], v[120:123]
	v_mfma_f32_16x16x32_bf16 v[116:119], v[196:199], v[212:215], v[116:119]
	v_mfma_f32_16x16x32_bf16 v[112:115], v[188:191], v[220:223], v[112:115]
	v_mfma_f32_16x16x32_bf16 v[108:111], v[196:199], v[220:223], v[108:111]
	v_mfma_f32_16x16x32_bf16 v[104:107], v[188:191], v[238:241], v[104:107]
	v_mfma_f32_16x16x32_bf16 v[100:103], v[196:199], v[238:241], v[100:103]
	s_barrier
; #define PG8_STAGE(bufoff, gbase, voff) do { _Pragma("unroll") for (int _i = 0; _i < 2; ++_i) \
;         __builtin_amdgcn_global_load_lds((const unsigned*)((const char*)(gbase) + (voff)[_i]), (PG8_LAS unsigned*)(lds + (bufoff) + ldsw + _i * 8192), 16, 0, 0); } while (0)
; #define PG8_LDA(dst, b, h) do { _Pragma("unroll") for (int m = 0; m < 4; ++m) _Pragma("unroll") for (int k = 0; k < 2; ++k) dst[m][k] = *(const PG8_LAS bf16x8*)(lds + PG8_SA(b, h) + aoff + m * 2048 + k * 1024); } while (0)
; #define PG8_LDB(dst, b, h) do { _Pragma("unroll") for (int n = 0; n < 2; ++n) _Pragma("unroll") for (int k = 0; k < 2; ++k) dst[n][k] = *(const PG8_LAS bf16x8*)(lds + PG8_SB(b, h) + boff + n * 2048 + k * 1024); } while (0)
; #define PG8_MMA(ai, bj, At, Bt) do { __builtin_amdgcn_s_setprio(1); _Pragma("unroll") for (int m = 0; m < 4; ++m) _Pragma("unroll") for (int n = 0; n < 2; ++n) _Pragma("unroll") for (int k = 0; k < 2; ++k) \
;         acc[ai][bj][m][n] = __builtin_amdgcn_mfma_f32_16x16x32_bf16(Bt[n][k], At[m][k], acc[ai][bj][m][n], 0, 0, 0); __builtin_amdgcn_s_setprio(0); } while (0)
; #define PG8_WAIT_V(n) asm volatile("s_waitcnt vmcnt(" #n ")" ::: "memory")
; #define PG8_WAIT_L(n) asm volatile("s_waitcnt lgkmcnt(" #n ")" ::: "memory")
; #define PG8_BAR __builtin_amdgcn_s_barrier()
; #define PG8_SCHED __builtin_amdgcn_sched_barrier(0)
; template <class Epi, class Sched, bool ALIGN_EPI = false, bool SP2 = false>
; __device__ __forceinline__ void gemm_phase(PG8_LAS unsigned char* lds, const Gemm g, const Sched& S, const Epi& E, const int tid) {
;     ...
;             PG8_WAIT_V(8); PG8_WAIT_L(0); PG8_BAR; PG8_MMA(0, 0, At, B0); PG8_MMA(0, 1, At, B1); PG8_BAR; PG8_SCHED;
;             PG8_LDA(At, 0, 1); PG8_STAGE(PG8_SB(0, 0), b2, voffB); PG8_STAGE(PG8_SB(0, 1), b2 + hstep, voffB); PG8_STAGE(PG8_SA(0, 0), a2, voffA);
;             PG8_WAIT_V(8); PG8_WAIT_L(0); PG8_BAR; PG8_MMA(1, 0, At, B0); PG8_MMA(1, 1, At, B1); PG8_BAR; PG8_SCHED;
;             PG8_LDB(B0, 1, 0); PG8_LDB(B1, 1, 1); PG8_SCHED; PG8_LDA(At, 1, 0); PG8_STAGE(PG8_SA(0, 1), a2 + hstep, voffA);
;             PG8_WAIT_V(8); PG8_WAIT_L(0); PG8_BAR; PG8_MMA(0, 0, At, B0); PG8_MMA(0, 1, At, B1); PG8_BAR; PG8_SCHED;
	s_add_i32 s55, s55, s43
	v_lshl_add_u64 v[146:147], s[26:27], 0, v[132:133]
	s_mov_b32 m0, s55
	ds_read_b128 v[200:203], v171 offset:16384
	ds_read_b128 v[204:207], v171 offset:17408
	ds_read_b128 v[208:211], v171 offset:18432
	ds_read_b128 v[212:215], v171 offset:19456
	ds_read_b128 v[216:219], v171 offset:20480
	ds_read_b128 v[220:223], v171 offset:21504
	ds_read_b128 v[224:227], v171 offset:22528
	ds_read_b128 v[238:241], v171 offset:23552
	global_load_lds_dwordx4 v[146:147], off
	s_add_i32 m0, s55, 0x2000
	s_add_u32 s56, s26, 0x40000
	v_lshl_add_u64 v[148:149], s[26:27], 0, v[136:137]
	s_addc_u32 s57, s27, 0
	s_add_i32 s55, s58, s43
	global_load_lds_dwordx4 v[148:149], off
	v_lshl_add_u64 v[150:151], s[56:57], 0, v[132:133]
	s_mov_b32 m0, s55
	v_lshl_add_u64 v[242:243], s[36:37], 0, v[134:135]
	global_load_lds_dwordx4 v[150:151], off
	v_lshl_add_u64 v[150:151], s[56:57], 0, v[136:137]
	s_add_i32 m0, s55, 0x2000
	s_nop 0
	global_load_lds_dwordx4 v[150:151], off
	v_lshl_add_u64 v[150:151], s[36:37], 0, v[0:1]
	s_mov_b32 m0, s25
	s_nop 0
	global_load_lds_dwordx4 v[150:151], off
	s_mov_b32 m0, s44
	s_nop 0
	global_load_lds_dwordx4 v[242:243], off
	s_waitcnt vmcnt(8)
	s_waitcnt lgkmcnt(0)
	s_barrier
	s_waitcnt lgkmcnt(0)
	v_mfma_f32_16x16x32_bf16 v[40:43], v[166:169], v[200:203], v[40:43]
	v_mfma_f32_16x16x32_bf16 v[36:39], v[176:179], v[200:203], v[36:39]
	v_mfma_f32_16x16x32_bf16 v[32:35], v[166:169], v[208:211], v[32:35]
	v_mfma_f32_16x16x32_bf16 v[28:31], v[176:179], v[208:211], v[28:31]
	v_mfma_f32_16x16x32_bf16 v[24:27], v[166:169], v[216:219], v[24:27]
	v_mfma_f32_16x16x32_bf16 v[20:23], v[176:179], v[216:219], v[20:23]
	v_mfma_f32_16x16x32_bf16 v[8:11], v[166:169], v[224:227], v[8:11]
	v_mfma_f32_16x16x32_bf16 v[4:7], v[176:179], v[224:227], v[4:7]
	v_mfma_f32_16x16x32_bf16 v[40:43], v[172:175], v[204:207], v[40:43]
	v_mfma_f32_16x16x32_bf16 v[36:39], v[180:183], v[204:207], v[36:39]
	v_mfma_f32_16x16x32_bf16 v[32:35], v[172:175], v[212:215], v[32:35]
	v_mfma_f32_16x16x32_bf16 v[28:31], v[180:183], v[212:215], v[28:31]
	v_mfma_f32_16x16x32_bf16 v[24:27], v[172:175], v[220:223], v[24:27]
	v_mfma_f32_16x16x32_bf16 v[20:23], v[180:183], v[220:223], v[20:23]
	v_mfma_f32_16x16x32_bf16 v[8:11], v[172:175], v[238:241], v[8:11]
	v_mfma_f32_16x16x32_bf16 v[4:7], v[180:183], v[238:241], v[4:7]
	v_mfma_f32_16x16x32_bf16 v[96:99], v[184:187], v[200:203], v[96:99]
	v_mfma_f32_16x16x32_bf16 v[92:95], v[192:195], v[200:203], v[92:95]
	v_mfma_f32_16x16x32_bf16 v[88:91], v[184:187], v[208:211], v[88:91]
	v_mfma_f32_16x16x32_bf16 v[84:87], v[192:195], v[208:211], v[84:87]
	v_mfma_f32_16x16x32_bf16 v[80:83], v[184:187], v[216:219], v[80:83]
	v_mfma_f32_16x16x32_bf16 v[76:79], v[192:195], v[216:219], v[76:79]
	v_mfma_f32_16x16x32_bf16 v[16:19], v[184:187], v[224:227], v[16:19]
	v_mfma_f32_16x16x32_bf16 v[12:15], v[192:195], v[224:227], v[12:15]
	v_mfma_f32_16x16x32_bf16 v[96:99], v[188:191], v[204:207], v[96:99]
	v_mfma_f32_16x16x32_bf16 v[92:95], v[196:199], v[204:207], v[92:95]
	v_mfma_f32_16x16x32_bf16 v[88:91], v[188:191], v[212:215], v[88:91]
	v_mfma_f32_16x16x32_bf16 v[84:87], v[196:199], v[212:215], v[84:87]
	v_mfma_f32_16x16x32_bf16 v[80:83], v[188:191], v[220:223], v[80:83]
	v_mfma_f32_16x16x32_bf16 v[76:79], v[196:199], v[220:223], v[76:79]
	v_mfma_f32_16x16x32_bf16 v[16:19], v[188:191], v[238:241], v[16:19]
	v_mfma_f32_16x16x32_bf16 v[12:15], v[196:199], v[238:241], v[12:15]
	s_barrier
	s_add_i32 s55, 0, 0x18000
	v_add_u32_e32 v153, s55, v165
	s_add_i32 s56, 0, 0x1c000
	ds_read_b128 v[166:169], v153
	ds_read_b128 v[172:175], v153 offset:1024
	ds_read_b128 v[176:179], v153 offset:2048
	ds_read_b128 v[180:183], v153 offset:3072
	v_add_u32_e32 v153, s56, v165
	ds_read_b128 v[184:187], v153
	ds_read_b128 v[188:191], v153 offset:1024
	ds_read_b128 v[192:195], v153 offset:2048
	ds_read_b128 v[196:199], v153 offset:3072
	s_add_u32 s36, s36, 0x40000
	s_addc_u32 s37, s37, 0
	s_mov_b32 m0, s45
	v_lshl_add_u64 v[244:245], s[36:37], 0, v[0:1]
	ds_read_b128 v[200:203], v171 offset:32768
	ds_read_b128 v[204:207], v171 offset:33792
	ds_read_b128 v[208:211], v171 offset:34816
	ds_read_b128 v[212:215], v171 offset:35840
	ds_read_b128 v[216:219], v171 offset:36864
	ds_read_b128 v[220:223], v171 offset:37888
	ds_read_b128 v[224:227], v171 offset:38912
	ds_read_b128 v[238:241], v171 offset:39936
	global_load_lds_dwordx4 v[244:245], off
	v_lshl_add_u64 v[244:245], s[36:37], 0, v[134:135]
	s_mov_b32 m0, s46
	s_nop 0
	global_load_lds_dwordx4 v[244:245], off
	s_waitcnt vmcnt(8)
	s_waitcnt lgkmcnt(0)
	s_barrier
; #define PG8_STAGE(bufoff, gbase, voff) do { _Pragma("unroll") for (int _i = 0; _i < 2; ++_i) \
;         __builtin_amdgcn_global_load_lds((const unsigned*)((const char*)(gbase) + (voff)[_i]), (PG8_LAS unsigned*)(lds + (bufoff) + ldsw + _i * 8192), 16, 0, 0); } while (0)
; #define PG8_LDA(dst, b, h) do { _Pragma("unroll") for (int m = 0; m < 4; ++m) _Pragma("unroll") for (int k = 0; k < 2; ++k) dst[m][k] = *(const PG8_LAS bf16x8*)(lds + PG8_SA(b, h) + aoff + m * 2048 + k * 1024); } while (0)
; #define PG8_LDB(dst, b, h) do { _Pragma("unroll") for (int n = 0; n < 2; ++n) _Pragma("unroll") for (int k = 0; k < 2; ++k) dst[n][k] = *(const PG8_LAS bf16x8*)(lds + PG8_SB(b, h) + boff + n * 2048 + k * 1024); } while (0)
; #define PG8_MMA(ai, bj, At, Bt) do { __builtin_amdgcn_s_setprio(1); _Pragma("unroll") for (int m = 0; m < 4; ++m) _Pragma("unroll") for (int n = 0; n < 2; ++n) _Pragma("unroll") for (int k = 0; k < 2; ++k) \
;         acc[ai][bj][m][n] = __builtin_amdgcn_mfma_f32_16x16x32_bf16(Bt[n][k], At[m][k], acc[ai][bj][m][n], 0, 0, 0); __builtin_amdgcn_s_setprio(0); } while (0)
; #define PG8_WAIT_V(n) asm volatile("s_waitcnt vmcnt(" #n ")" ::: "memory")
; #define PG8_WAIT_L(n) asm volatile("s_waitcnt lgkmcnt(" #n ")" ::: "memory")
; template <class Epi, class Sched, bool ALIGN_EPI = false, bool SP2 = false>
; __device__ __forceinline__ void gemm_phase(PG8_LAS unsigned char* lds, const Gemm g, const Sched& S, const Epi& E, const int tid) {
;     ...
;             PG8_WAIT_V(8); PG8_WAIT_L(0); PG8_BAR; PG8_MMA(0, 0, At, B0); PG8_MMA(0, 1, At, B1); PG8_BAR; PG8_SCHED;
;             PG8_LDA(At, 0, 1); PG8_STAGE(PG8_SB(0, 0), b2, voffB); PG8_STAGE(PG8_SB(0, 1), b2 + hstep, voffB); PG8_STAGE(PG8_SA(0, 0), a2, voffA);
;             PG8_WAIT_V(8); PG8_WAIT_L(0); PG8_BAR; PG8_MMA(1, 0, At, B0); PG8_MMA(1, 1, At, B1); PG8_BAR; PG8_SCHED;
;             PG8_LDB(B0, 1, 0); PG8_LDB(B1, 1, 1); PG8_SCHED; PG8_LDA(At, 1, 0); PG8_STAGE(PG8_SA(0, 1), a2 + hstep, voffA);
;             PG8_WAIT_V(8); PG8_WAIT_L(0); PG8_BAR; PG8_MMA(0, 0, At, B0); PG8_MMA(0, 1, At, B1); PG8_BAR; PG8_SCHED;
;             PG8_LDA(At, 1, 1); PG8_STAGE(PG8_SB(1, 0), b3, voffB); PG8_STAGE(PG8_SB(1, 1), b3 + hstep, voffB); PG8_STAGE(PG8_SA(1, 0), a3, voffA);
;             PG8_WAIT_V(8); PG8_WAIT_L(0); PG8_BAR; PG8_MMA(1, 0, At, B0); PG8_MMA(1, 1, At, B1); PG8_BAR; PG8_SCHED;
	s_waitcnt lgkmcnt(0)
	v_mfma_f32_16x16x32_bf16 v[72:75], v[166:169], v[200:203], v[72:75]
	v_mfma_f32_16x16x32_bf16 v[68:71], v[176:179], v[200:203], v[68:71]
	v_mfma_f32_16x16x32_bf16 v[64:67], v[166:169], v[208:211], v[64:67]
	v_mfma_f32_16x16x32_bf16 v[60:63], v[176:179], v[208:211], v[60:63]
	v_mfma_f32_16x16x32_bf16 v[56:59], v[166:169], v[216:219], v[56:59]
	v_mfma_f32_16x16x32_bf16 v[52:55], v[176:179], v[216:219], v[52:55]
	v_mfma_f32_16x16x32_bf16 v[48:51], v[166:169], v[224:227], v[48:51]
	v_mfma_f32_16x16x32_bf16 v[44:47], v[176:179], v[224:227], v[44:47]
	v_mfma_f32_16x16x32_bf16 v[72:75], v[172:175], v[204:207], v[72:75]
	v_mfma_f32_16x16x32_bf16 v[68:71], v[180:183], v[204:207], v[68:71]
	v_mfma_f32_16x16x32_bf16 v[64:67], v[172:175], v[212:215], v[64:67]
	v_mfma_f32_16x16x32_bf16 v[60:63], v[180:183], v[212:215], v[60:63]
	v_mfma_f32_16x16x32_bf16 v[56:59], v[172:175], v[220:223], v[56:59]
	v_mfma_f32_16x16x32_bf16 v[52:55], v[180:183], v[220:223], v[52:55]
	v_mfma_f32_16x16x32_bf16 v[48:51], v[172:175], v[238:241], v[48:51]
	v_mfma_f32_16x16x32_bf16 v[44:47], v[180:183], v[238:241], v[44:47]
	v_mfma_f32_16x16x32_bf16 v[128:131], v[184:187], v[200:203], v[128:131]
	v_mfma_f32_16x16x32_bf16 v[124:127], v[192:195], v[200:203], v[124:127]
	v_mfma_f32_16x16x32_bf16 v[120:123], v[184:187], v[208:211], v[120:123]
	v_mfma_f32_16x16x32_bf16 v[116:119], v[192:195], v[208:211], v[116:119]
	v_mfma_f32_16x16x32_bf16 v[112:115], v[184:187], v[216:219], v[112:115]
	v_mfma_f32_16x16x32_bf16 v[108:111], v[192:195], v[216:219], v[108:111]
	v_mfma_f32_16x16x32_bf16 v[104:107], v[184:187], v[224:227], v[104:107]
	v_mfma_f32_16x16x32_bf16 v[100:103], v[192:195], v[224:227], v[100:103]
	v_mfma_f32_16x16x32_bf16 v[128:131], v[188:191], v[204:207], v[128:131]
	v_mfma_f32_16x16x32_bf16 v[124:127], v[196:199], v[204:207], v[124:127]
	v_mfma_f32_16x16x32_bf16 v[120:123], v[188:191], v[212:215], v[120:123]
	v_mfma_f32_16x16x32_bf16 v[116:119], v[196:199], v[212:215], v[116:119]
	v_mfma_f32_16x16x32_bf16 v[112:115], v[188:191], v[220:223], v[112:115]
	v_mfma_f32_16x16x32_bf16 v[108:111], v[196:199], v[220:223], v[108:111]
	v_mfma_f32_16x16x32_bf16 v[104:107], v[188:191], v[238:241], v[104:107]
	v_mfma_f32_16x16x32_bf16 v[100:103], v[196:199], v[238:241], v[100:103]
	s_barrier
	s_add_i32 s36, s55, s43
	v_lshl_add_u64 v[146:147], v[146:147], 0, s[0:1]
	s_mov_b32 m0, s36
	ds_read_b128 v[200:203], v171 offset:49152
	ds_read_b128 v[204:207], v171 offset:50176
	ds_read_b128 v[208:211], v171 offset:51200
	ds_read_b128 v[212:215], v171 offset:52224
	ds_read_b128 v[216:219], v171 offset:53248
	ds_read_b128 v[220:223], v171 offset:54272
	ds_read_b128 v[224:227], v171 offset:55296
	ds_read_b128 v[238:241], v171 offset:56320
	global_load_lds_dwordx4 v[146:147], off
	s_add_i32 m0, s36, 0x2000
	s_add_u32 s26, s26, 0x40080
	v_lshl_add_u64 v[146:147], v[148:149], 0, s[0:1]
	s_addc_u32 s27, s27, 0
	s_add_i32 s36, s56, s43
	global_load_lds_dwordx4 v[146:147], off
	v_lshl_add_u64 v[146:147], s[26:27], 0, v[132:133]
	s_mov_b32 m0, s36
	s_nop 0
	global_load_lds_dwordx4 v[146:147], off
	v_lshl_add_u64 v[146:147], s[26:27], 0, v[136:137]
	s_add_i32 m0, s36, 0x2000
	s_nop 0
	global_load_lds_dwordx4 v[146:147], off
	v_lshl_add_u64 v[146:147], v[150:151], 0, s[0:1]
	s_mov_b32 m0, s48
	s_nop 0
	global_load_lds_dwordx4 v[146:147], off
	v_lshl_add_u64 v[146:147], v[242:243], 0, s[0:1]
	s_mov_b32 m0, s49
	s_nop 0
	global_load_lds_dwordx4 v[146:147], off
	s_waitcnt vmcnt(8)
	s_waitcnt lgkmcnt(0)
	s_barrier
	s_waitcnt lgkmcnt(0)
	v_mfma_f32_16x16x32_bf16 v[40:43], v[166:169], v[200:203], v[40:43]
	v_mfma_f32_16x16x32_bf16 v[36:39], v[176:179], v[200:203], v[36:39]
	v_mfma_f32_16x16x32_bf16 v[32:35], v[166:169], v[208:211], v[32:35]
	v_mfma_f32_16x16x32_bf16 v[28:31], v[176:179], v[208:211], v[28:31]
	v_mfma_f32_16x16x32_bf16 v[24:27], v[166:169], v[216:219], v[24:27]
	v_mfma_f32_16x16x32_bf16 v[20:23], v[176:179], v[216:219], v[20:23]
	v_mfma_f32_16x16x32_bf16 v[8:11], v[166:169], v[224:227], v[8:11]
	v_mfma_f32_16x16x32_bf16 v[4:7], v[176:179], v[224:227], v[4:7]
	v_mfma_f32_16x16x32_bf16 v[40:43], v[172:175], v[204:207], v[40:43]
	v_mfma_f32_16x16x32_bf16 v[36:39], v[180:183], v[204:207], v[36:39]
	v_mfma_f32_16x16x32_bf16 v[32:35], v[172:175], v[212:215], v[32:35]
	v_mfma_f32_16x16x32_bf16 v[28:31], v[180:183], v[212:215], v[28:31]
	v_mfma_f32_16x16x32_bf16 v[24:27], v[172:175], v[220:223], v[24:27]
	v_mfma_f32_16x16x32_bf16 v[20:23], v[180:183], v[220:223], v[20:23]
	v_mfma_f32_16x16x32_bf16 v[8:11], v[172:175], v[238:241], v[8:11]
	v_mfma_f32_16x16x32_bf16 v[4:7], v[180:183], v[238:241], v[4:7]
	v_mfma_f32_16x16x32_bf16 v[96:99], v[184:187], v[200:203], v[96:99]
	v_mfma_f32_16x16x32_bf16 v[92:95], v[192:195], v[200:203], v[92:95]
	v_mfma_f32_16x16x32_bf16 v[88:91], v[184:187], v[208:211], v[88:91]
	v_mfma_f32_16x16x32_bf16 v[84:87], v[192:195], v[208:211], v[84:87]
	v_mfma_f32_16x16x32_bf16 v[80:83], v[184:187], v[216:219], v[80:83]
	v_mfma_f32_16x16x32_bf16 v[76:79], v[192:195], v[216:219], v[76:79]
	v_mfma_f32_16x16x32_bf16 v[16:19], v[184:187], v[224:227], v[16:19]
	v_mfma_f32_16x16x32_bf16 v[12:15], v[192:195], v[224:227], v[12:15]
	v_mfma_f32_16x16x32_bf16 v[96:99], v[188:191], v[204:207], v[96:99]
	v_mfma_f32_16x16x32_bf16 v[92:95], v[196:199], v[204:207], v[92:95]
	v_mfma_f32_16x16x32_bf16 v[88:91], v[188:191], v[212:215], v[88:91]
	v_mfma_f32_16x16x32_bf16 v[84:87], v[196:199], v[212:215], v[84:87]
	v_mfma_f32_16x16x32_bf16 v[80:83], v[188:191], v[220:223], v[80:83]
	v_mfma_f32_16x16x32_bf16 v[76:79], v[196:199], v[220:223], v[76:79]
	v_mfma_f32_16x16x32_bf16 v[16:19], v[188:191], v[238:241], v[16:19]
	v_mfma_f32_16x16x32_bf16 v[12:15], v[196:199], v[238:241], v[12:15]
	s_barrier
	s_add_i32 s54, s54, 2
	s_add_u32 s2, s2, 0x100
	s_addc_u32 s3, s3, 0
	s_add_u32 s52, s52, 0x100
	s_addc_u32 s53, s53, 0
	s_cmp_gt_u32 s54, 13
	s_cbranch_scc0 .LBB0_293
	s_setprio 0
	s_and_b64 vcc, exec, s[10:11]
	s_cbranch_vccz .LBB0_296
	s_barrier

; #define PG8_STAGE(bufoff, gbase, voff) do { _Pragma("unroll") for (int _i = 0; _i < 2; ++_i) \
;         __builtin_amdgcn_global_load_lds((const unsigned*)((const char*)(gbase) + (voff)[_i]), (PG8_LAS unsigned*)(lds + (bufoff) + ldsw + _i * 8192), 16, 0, 0); } while (0)
; #define PG8_LDA(dst, b, h) do { _Pragma("unroll") for (int m = 0; m < 4; ++m) _Pragma("unroll") for (int k = 0; k < 2; ++k) dst[m][k] = *(const PG8_LAS bf16x8*)(lds + PG8_SA(b, h) + aoff + m * 2048 + k * 1024); } while (0)
; #define PG8_LDB(dst, b, h) do { _Pragma("unroll") for (int n = 0; n < 2; ++n) _Pragma("unroll") for (int k = 0; k < 2; ++k) dst[n][k] = *(const PG8_LAS bf16x8*)(lds + PG8_SB(b, h) + boff + n * 2048 + k * 1024); } while (0)
; #define PG8_WAIT_V(n) asm volatile("s_waitcnt vmcnt(" #n ")" ::: "memory")
; #define PG8_WAIT_L(n) asm volatile("s_waitcnt lgkmcnt(" #n ")" ::: "memory")
; #define PG8_BAR __builtin_amdgcn_s_barrier()
; template <class Epi, class Sched, bool ALIGN_EPI = false, bool SP2 = false>
; __device__ __forceinline__ void gemm_phase(PG8_LAS unsigned char* lds, const Gemm g, const Sched& S, const Epi& E, const int tid) {
;     ...
;         const bool has_next = S.next(ui + 1, nxt);
;         const char* nA = has_next ? (const char*)g.A + (size_t)nxt.pm * tstep : cA; const char* nB = has_next ? (const char*)g.Bt + (size_t)nxt.pn * tstep : cB;
;         for (int t = 0; t < nt; t += 2) {
;             const bool last = (t == nt - 2);
;             const char* a1 = cA + (size_t)(t + 1) * kstep;
;             const char* a2 = last ? nA : cA + (size_t)(t + 2) * kstep; const char* b2 = last ? nB : cB + (size_t)(t + 2) * kstep;
;             const char* a3 = a2 + kstep; const char* b3 = b2 + kstep;
;             if (last && has_next) S.a_ready(nxt);
;             if constexpr (SP2) {
;             PG8_LDB(B0, 0, 0); PG8_LDB(B1, 0, 1); PG8_SCHED; PG8_LDA(At, 0, 0); PG8_STAGE(PG8_SA(1, 1), a1 + hstep, voffA);
;             PG8_WAIT_V(8); PG8_WAIT_L(0); PG8_BAR; PG8_MMA(0, 0, At, B0); PG8_MMA(0, 1, At, B1); PG8_BAR; PG8_SCHED;
;     ...
; #pragma unroll
;         for (int a = 0; a < 2; ++a)
; #pragma unroll
;             for (int b = 0; b < 2; ++b)
; #pragma unroll
;                 for (int m = 0; m < 4; ++m)
; #pragma unroll
;                     for (int n = 0; n < 2; ++n) acc[a][b][m][n] = (f32x4){0.f, 0.f, 0.f, 0.f};
;         cur = nxt; cA = nA; cB = nB; ++ui;
.LBB0_475:
	s_add_u32 s6, s6, 0x80
	s_addc_u32 s7, s7, 0
	s_add_u32 s78, s58, 0x100
	v_mov_b32_e32 v4, 0
	s_addc_u32 s79, s59, 0
	s_mov_b32 s58, 0
	v_mov_b64_e32 v[4:5], 0
	v_mov_b64_e32 v[6:7], 0
	v_mov_b64_e32 v[8:9], 0
	v_mov_b64_e32 v[10:11], 0
	v_mov_b64_e32 v[12:13], 0
	v_mov_b64_e32 v[14:15], 0
	v_mov_b64_e32 v[16:17], 0
	v_mov_b64_e32 v[18:19], 0
	v_mov_b64_e32 v[20:21], 0
	v_mov_b64_e32 v[22:23], 0
	v_mov_b64_e32 v[24:25], 0
	v_mov_b64_e32 v[26:27], 0
	v_mov_b64_e32 v[28:29], 0
	v_mov_b64_e32 v[30:31], 0
	v_mov_b64_e32 v[32:33], 0
	v_mov_b64_e32 v[34:35], 0
	v_mov_b64_e32 v[36:37], 0
	v_mov_b64_e32 v[38:39], 0
	v_mov_b64_e32 v[40:41], 0
	v_mov_b64_e32 v[42:43], 0
	v_mov_b64_e32 v[44:45], 0
	v_mov_b64_e32 v[46:47], 0
	v_mov_b64_e32 v[48:49], 0
	v_mov_b64_e32 v[50:51], 0
	v_mov_b64_e32 v[52:53], 0
	v_mov_b64_e32 v[54:55], 0
	v_mov_b64_e32 v[56:57], 0
	v_mov_b64_e32 v[58:59], 0
	v_mov_b64_e32 v[60:61], 0
	v_mov_b64_e32 v[62:63], 0
	v_mov_b64_e32 v[64:65], 0
	v_mov_b64_e32 v[66:67], 0
	v_mov_b64_e32 v[68:69], 0
	v_mov_b64_e32 v[70:71], 0
	v_mov_b64_e32 v[72:73], 0
	v_mov_b64_e32 v[74:75], 0
	v_mov_b64_e32 v[76:77], 0
	v_mov_b64_e32 v[78:79], 0
	v_mov_b64_e32 v[80:81], 0
	v_mov_b64_e32 v[82:83], 0
	v_mov_b64_e32 v[84:85], 0
	v_mov_b64_e32 v[86:87], 0
	v_mov_b64_e32 v[88:89], 0
	v_mov_b64_e32 v[90:91], 0
	v_mov_b64_e32 v[92:93], 0
	v_mov_b64_e32 v[94:95], 0
	v_mov_b64_e32 v[96:97], 0
	v_mov_b64_e32 v[98:99], 0
	v_mov_b64_e32 v[100:101], 0
	v_mov_b64_e32 v[102:103], 0
	v_mov_b64_e32 v[104:105], 0
	v_mov_b64_e32 v[106:107], 0
	v_mov_b64_e32 v[108:109], 0
	v_mov_b64_e32 v[110:111], 0
	v_mov_b64_e32 v[112:113], 0
	v_mov_b64_e32 v[114:115], 0
	v_mov_b64_e32 v[116:117], 0
	v_mov_b64_e32 v[118:119], 0
	v_mov_b64_e32 v[120:121], 0
	v_mov_b64_e32 v[122:123], 0
	v_mov_b64_e32 v[124:125], 0
	v_mov_b64_e32 v[126:127], 0
	v_mov_b64_e32 v[128:129], 0
	v_mov_b64_e32 v[130:131], 0
	s_cmp_lt_u32 s92, 4
	s_cbranch_scc1 .Lprio_skip2
	s_setprio 1
.Lprio_skip2:
.LBB0_476:
	s_add_i32 s80, s58, 2
	s_add_u32 s81, s6, 0x80
	s_addc_u32 s59, s7, 0
	s_add_i32 s87, 0, 0x10000
	s_cmp_eq_u32 s70, s58
	s_cselect_b32 s59, s55, s59
	s_cselect_b32 s58, s54, s81
	v_add_u32_e32 v144, s87, v184
	s_cselect_b32 s83, s57, s79
	s_cselect_b32 s82, s56, s78
	s_add_i32 s81, 0, 0x14000
	ds_read_b128 v[132:135], v144
	ds_read_b128 v[136:139], v144 offset:1024
	ds_read_b128 v[140:143], v144 offset:2048
	ds_read_b128 v[174:177], v144 offset:3072
	v_add_u32_e32 v144, s81, v184
	ds_read_b128 v[178:181], v144
	ds_read_b128 v[188:191], v144 offset:1024
	ds_read_b128 v[192:195], v144 offset:2048
	ds_read_b128 v[196:199], v144 offset:3072
	v_lshl_add_u64 v[144:145], s[6:7], 0, v[170:171]
	s_add_i32 m0, s62, 0xc000
	ds_read_b128 v[200:203], v186
	ds_read_b128 v[204:207], v186 offset:1024
	ds_read_b128 v[208:211], v186 offset:2048
	ds_read_b128 v[212:215], v186 offset:3072
	ds_read_b128 v[216:219], v186 offset:4096
	ds_read_b128 v[220:223], v186 offset:5120
	ds_read_b128 v[224:227], v186 offset:6144
	ds_read_b128 v[238:241], v186 offset:7168
	global_load_lds_dwordx4 v[144:145], off
	v_lshl_add_u64 v[144:145], s[6:7], 0, v[172:173]
	s_add_i32 m0, s62, 0xe000
	s_nop 0
	global_load_lds_dwordx4 v[144:145], off
	s_waitcnt vmcnt(8)
	s_waitcnt lgkmcnt(0)
	s_barrier
	s_waitcnt lgkmcnt(0)
	v_mfma_f32_16x16x32_bf16 v[128:131], v[132:135], v[200:203], v[128:131]
	v_mfma_f32_16x16x32_bf16 v[124:127], v[140:143], v[200:203], v[124:127]
	v_mfma_f32_16x16x32_bf16 v[112:115], v[132:135], v[208:211], v[112:115]
	v_mfma_f32_16x16x32_bf16 v[108:111], v[140:143], v[208:211], v[108:111]
	v_mfma_f32_16x16x32_bf16 v[96:99], v[132:135], v[216:219], v[96:99]
	v_mfma_f32_16x16x32_bf16 v[92:95], v[140:143], v[216:219], v[92:95]
	v_mfma_f32_16x16x32_bf16 v[80:83], v[132:135], v[224:227], v[80:83]
	v_mfma_f32_16x16x32_bf16 v[76:79], v[140:143], v[224:227], v[76:79]
	v_mfma_f32_16x16x32_bf16 v[128:131], v[136:139], v[204:207], v[128:131]
	v_mfma_f32_16x16x32_bf16 v[124:127], v[174:177], v[204:207], v[124:127]
	v_mfma_f32_16x16x32_bf16 v[112:115], v[136:139], v[212:215], v[112:115]
	v_mfma_f32_16x16x32_bf16 v[108:111], v[174:177], v[212:215], v[108:111]
	v_mfma_f32_16x16x32_bf16 v[96:99], v[136:139], v[220:223], v[96:99]
	v_mfma_f32_16x16x32_bf16 v[92:95], v[174:177], v[220:223], v[92:95]
	v_mfma_f32_16x16x32_bf16 v[80:83], v[136:139], v[238:241], v[80:83]
	v_mfma_f32_16x16x32_bf16 v[76:79], v[174:177], v[238:241], v[76:79]
	v_mfma_f32_16x16x32_bf16 v[120:123], v[178:181], v[200:203], v[120:123]
	v_mfma_f32_16x16x32_bf16 v[116:119], v[192:195], v[200:203], v[116:119]
	v_mfma_f32_16x16x32_bf16 v[104:107], v[178:181], v[208:211], v[104:107]
	v_mfma_f32_16x16x32_bf16 v[100:103], v[192:195], v[208:211], v[100:103]
	v_mfma_f32_16x16x32_bf16 v[88:91], v[178:181], v[216:219], v[88:91]
	v_mfma_f32_16x16x32_bf16 v[84:87], v[192:195], v[216:219], v[84:87]
	v_mfma_f32_16x16x32_bf16 v[72:75], v[178:181], v[224:227], v[72:75]
	v_mfma_f32_16x16x32_bf16 v[68:71], v[192:195], v[224:227], v[68:71]
	v_mfma_f32_16x16x32_bf16 v[120:123], v[188:191], v[204:207], v[120:123]
	v_mfma_f32_16x16x32_bf16 v[116:119], v[196:199], v[204:207], v[116:119]
	v_mfma_f32_16x16x32_bf16 v[104:107], v[188:191], v[212:215], v[104:107]
	v_mfma_f32_16x16x32_bf16 v[100:103], v[196:199], v[212:215], v[100:103]
	v_mfma_f32_16x16x32_bf16 v[88:91], v[188:191], v[220:223], v[88:91]
	v_mfma_f32_16x16x32_bf16 v[84:87], v[196:199], v[220:223], v[84:87]
	v_mfma_f32_16x16x32_bf16 v[72:75], v[188:191], v[238:241], v[72:75]
	v_mfma_f32_16x16x32_bf16 v[68:71], v[196:199], v[238:241], v[68:71]
	s_barrier
; #define PG8_STAGE(bufoff, gbase, voff) do { _Pragma("unroll") for (int _i = 0; _i < 2; ++_i) \
;         __builtin_amdgcn_global_load_lds((const unsigned*)((const char*)(gbase) + (voff)[_i]), (PG8_LAS unsigned*)(lds + (bufoff) + ldsw + _i * 8192), 16, 0, 0); } while (0)
; #define PG8_LDA(dst, b, h) do { _Pragma("unroll") for (int m = 0; m < 4; ++m) _Pragma("unroll") for (int k = 0; k < 2; ++k) dst[m][k] = *(const PG8_LAS bf16x8*)(lds + PG8_SA(b, h) + aoff + m * 2048 + k * 1024); } while (0)
; #define PG8_LDB(dst, b, h) do { _Pragma("unroll") for (int n = 0; n < 2; ++n) _Pragma("unroll") for (int k = 0; k < 2; ++k) dst[n][k] = *(const PG8_LAS bf16x8*)(lds + PG8_SB(b, h) + boff + n * 2048 + k * 1024); } while (0)
; #define PG8_MMA(ai, bj, At, Bt) do { __builtin_amdgcn_s_setprio(1); _Pragma("unroll") for (int m = 0; m < 4; ++m) _Pragma("unroll") for (int n = 0; n < 2; ++n) _Pragma("unroll") for (int k = 0; k < 2; ++k) \
;         acc[ai][bj][m][n] = __builtin_amdgcn_mfma_f32_16x16x32_bf16(Bt[n][k], At[m][k], acc[ai][bj][m][n], 0, 0, 0); __builtin_amdgcn_s_setprio(0); } while (0)
; #define PG8_WAIT_V(n) asm volatile("s_waitcnt vmcnt(" #n ")" ::: "memory")
; #define PG8_WAIT_L(n) asm volatile("s_waitcnt lgkmcnt(" #n ")" ::: "memory")
; #define PG8_BAR __builtin_amdgcn_s_barrier()
; #define PG8_SCHED __builtin_amdgcn_sched_barrier(0)
; template <class Epi, class Sched, bool ALIGN_EPI = false, bool SP2 = false>
; __device__ __forceinline__ void gemm_phase(PG8_LAS unsigned char* lds, const Gemm g, const Sched& S, const Epi& E, const int tid) {
;     ...
;             PG8_WAIT_V(8); PG8_WAIT_L(0); PG8_BAR; PG8_MMA(0, 0, At, B0); PG8_MMA(0, 1, At, B1); PG8_BAR; PG8_SCHED;
;             PG8_LDA(At, 0, 1); PG8_STAGE(PG8_SB(0, 0), b2, voffB); PG8_STAGE(PG8_SB(0, 1), b2 + hstep, voffB); PG8_STAGE(PG8_SA(0, 0), a2, voffA);
;             PG8_WAIT_V(8); PG8_WAIT_L(0); PG8_BAR; PG8_MMA(1, 0, At, B0); PG8_MMA(1, 1, At, B1); PG8_BAR; PG8_SCHED;
;             PG8_LDB(B0, 1, 0); PG8_LDB(B1, 1, 1); PG8_SCHED; PG8_LDA(At, 1, 0); PG8_STAGE(PG8_SA(0, 1), a2 + hstep, voffA);
;             PG8_WAIT_V(8); PG8_WAIT_L(0); PG8_BAR; PG8_MMA(0, 0, At, B0); PG8_MMA(0, 1, At, B1); PG8_BAR; PG8_SCHED;
	s_add_i32 s87, s87, s61
	v_lshl_add_u64 v[144:145], s[82:83], 0, v[146:147]
	s_mov_b32 m0, s87
	ds_read_b128 v[200:203], v186 offset:16384
	ds_read_b128 v[204:207], v186 offset:17408
	ds_read_b128 v[208:211], v186 offset:18432
	ds_read_b128 v[212:215], v186 offset:19456
	ds_read_b128 v[216:219], v186 offset:20480
	ds_read_b128 v[220:223], v186 offset:21504
	ds_read_b128 v[224:227], v186 offset:22528
	ds_read_b128 v[238:241], v186 offset:23552
	global_load_lds_dwordx4 v[144:145], off
	s_add_i32 m0, s87, 0x2000
	v_lshl_add_u64 v[242:243], s[82:83], 0, v[168:169]
	s_add_u32 s82, s82, s14
	s_addc_u32 s83, s83, 0
	s_add_i32 s81, s81, s61
	global_load_lds_dwordx4 v[242:243], off
	v_lshl_add_u64 v[244:245], s[82:83], 0, v[146:147]
	s_mov_b32 m0, s81
	v_lshl_add_u64 v[246:247], s[82:83], 0, v[168:169]
	global_load_lds_dwordx4 v[244:245], off
	s_add_i32 m0, s81, 0x2000
	v_lshl_add_u64 v[248:249], s[58:59], 0, v[0:1]
	global_load_lds_dwordx4 v[246:247], off
	s_mov_b32 m0, s62
	v_lshl_add_u64 v[148:149], s[58:59], 0, v[166:167]
	global_load_lds_dwordx4 v[248:249], off
	s_mov_b32 m0, s63
	s_nop 0
	global_load_lds_dwordx4 v[148:149], off
	s_waitcnt vmcnt(8)
	s_waitcnt lgkmcnt(0)
	s_barrier
	s_waitcnt lgkmcnt(0)
	v_mfma_f32_16x16x32_bf16 v[64:67], v[132:135], v[200:203], v[64:67]
	v_mfma_f32_16x16x32_bf16 v[60:63], v[140:143], v[200:203], v[60:63]
	v_mfma_f32_16x16x32_bf16 v[48:51], v[132:135], v[208:211], v[48:51]
	v_mfma_f32_16x16x32_bf16 v[44:47], v[140:143], v[208:211], v[44:47]
	v_mfma_f32_16x16x32_bf16 v[32:35], v[132:135], v[216:219], v[32:35]
	v_mfma_f32_16x16x32_bf16 v[28:31], v[140:143], v[216:219], v[28:31]
	v_mfma_f32_16x16x32_bf16 v[16:19], v[132:135], v[224:227], v[16:19]
	v_mfma_f32_16x16x32_bf16 v[12:15], v[140:143], v[224:227], v[12:15]
	v_mfma_f32_16x16x32_bf16 v[64:67], v[136:139], v[204:207], v[64:67]
	v_mfma_f32_16x16x32_bf16 v[60:63], v[174:177], v[204:207], v[60:63]
	v_mfma_f32_16x16x32_bf16 v[48:51], v[136:139], v[212:215], v[48:51]
	v_mfma_f32_16x16x32_bf16 v[44:47], v[174:177], v[212:215], v[44:47]
	v_mfma_f32_16x16x32_bf16 v[32:35], v[136:139], v[220:223], v[32:35]
	v_mfma_f32_16x16x32_bf16 v[28:31], v[174:177], v[220:223], v[28:31]
	v_mfma_f32_16x16x32_bf16 v[16:19], v[136:139], v[238:241], v[16:19]
	v_mfma_f32_16x16x32_bf16 v[12:15], v[174:177], v[238:241], v[12:15]
	v_mfma_f32_16x16x32_bf16 v[56:59], v[178:181], v[200:203], v[56:59]
	v_mfma_f32_16x16x32_bf16 v[52:55], v[192:195], v[200:203], v[52:55]
	v_mfma_f32_16x16x32_bf16 v[40:43], v[178:181], v[208:211], v[40:43]
	v_mfma_f32_16x16x32_bf16 v[36:39], v[192:195], v[208:211], v[36:39]
	v_mfma_f32_16x16x32_bf16 v[24:27], v[178:181], v[216:219], v[24:27]
	v_mfma_f32_16x16x32_bf16 v[20:23], v[192:195], v[216:219], v[20:23]
	v_mfma_f32_16x16x32_bf16 v[8:11], v[178:181], v[224:227], v[8:11]
	v_mfma_f32_16x16x32_bf16 v[4:7], v[192:195], v[224:227], v[4:7]
	v_mfma_f32_16x16x32_bf16 v[56:59], v[188:191], v[204:207], v[56:59]
	v_mfma_f32_16x16x32_bf16 v[52:55], v[196:199], v[204:207], v[52:55]
	v_mfma_f32_16x16x32_bf16 v[40:43], v[188:191], v[212:215], v[40:43]
	v_mfma_f32_16x16x32_bf16 v[36:39], v[196:199], v[212:215], v[36:39]
	v_mfma_f32_16x16x32_bf16 v[24:27], v[188:191], v[220:223], v[24:27]
	v_mfma_f32_16x16x32_bf16 v[20:23], v[196:199], v[220:223], v[20:23]
	v_mfma_f32_16x16x32_bf16 v[8:11], v[188:191], v[238:241], v[8:11]
	v_mfma_f32_16x16x32_bf16 v[4:7], v[196:199], v[238:241], v[4:7]
	s_barrier
	s_add_i32 s81, 0, 0x18000
	v_add_u32_e32 v150, s81, v184
	s_add_i32 s82, 0, 0x1c000
	ds_read_b128 v[132:135], v150
	ds_read_b128 v[136:139], v150 offset:1024
	ds_read_b128 v[140:143], v150 offset:2048
	ds_read_b128 v[174:177], v150 offset:3072
	v_add_u32_e32 v150, s82, v184
	ds_read_b128 v[178:181], v150
	ds_read_b128 v[188:191], v150 offset:1024
	ds_read_b128 v[192:195], v150 offset:2048
	ds_read_b128 v[196:199], v150 offset:3072
	s_add_u32 s58, s58, s14
	s_addc_u32 s59, s59, 0
	s_mov_b32 m0, s64
	v_lshl_add_u64 v[150:151], s[58:59], 0, v[0:1]
	ds_read_b128 v[200:203], v186 offset:32768
	ds_read_b128 v[204:207], v186 offset:33792
	ds_read_b128 v[208:211], v186 offset:34816
	ds_read_b128 v[212:215], v186 offset:35840
	ds_read_b128 v[216:219], v186 offset:36864
	ds_read_b128 v[220:223], v186 offset:37888
	ds_read_b128 v[224:227], v186 offset:38912
	ds_read_b128 v[238:241], v186 offset:39936
	global_load_lds_dwordx4 v[150:151], off
	v_lshl_add_u64 v[150:151], s[58:59], 0, v[166:167]
	s_mov_b32 m0, s65
	s_nop 0
	global_load_lds_dwordx4 v[150:151], off
	s_waitcnt vmcnt(8)
	s_waitcnt lgkmcnt(0)
	s_barrier
; #define PG8_STAGE(bufoff, gbase, voff) do { _Pragma("unroll") for (int _i = 0; _i < 2; ++_i) \
;         __builtin_amdgcn_global_load_lds((const unsigned*)((const char*)(gbase) + (voff)[_i]), (PG8_LAS unsigned*)(lds + (bufoff) + ldsw + _i * 8192), 16, 0, 0); } while (0)
; #define PG8_LDA(dst, b, h) do { _Pragma("unroll") for (int m = 0; m < 4; ++m) _Pragma("unroll") for (int k = 0; k < 2; ++k) dst[m][k] = *(const PG8_LAS bf16x8*)(lds + PG8_SA(b, h) + aoff + m * 2048 + k * 1024); } while (0)
; #define PG8_LDB(dst, b, h) do { _Pragma("unroll") for (int n = 0; n < 2; ++n) _Pragma("unroll") for (int k = 0; k < 2; ++k) dst[n][k] = *(const PG8_LAS bf16x8*)(lds + PG8_SB(b, h) + boff + n * 2048 + k * 1024); } while (0)
; #define PG8_MMA(ai, bj, At, Bt) do { __builtin_amdgcn_s_setprio(1); _Pragma("unroll") for (int m = 0; m < 4; ++m) _Pragma("unroll") for (int n = 0; n < 2; ++n) _Pragma("unroll") for (int k = 0; k < 2; ++k) \
;         acc[ai][bj][m][n] = __builtin_amdgcn_mfma_f32_16x16x32_bf16(Bt[n][k], At[m][k], acc[ai][bj][m][n], 0, 0, 0); __builtin_amdgcn_s_setprio(0); } while (0)
; #define PG8_WAIT_V(n) asm volatile("s_waitcnt vmcnt(" #n ")" ::: "memory")
; #define PG8_WAIT_L(n) asm volatile("s_waitcnt lgkmcnt(" #n ")" ::: "memory")
; template <class Epi, class Sched, bool ALIGN_EPI = false, bool SP2 = false>
; __device__ __forceinline__ void gemm_phase(PG8_LAS unsigned char* lds, const Gemm g, const Sched& S, const Epi& E, const int tid) {
;     ...
;             PG8_WAIT_V(8); PG8_WAIT_L(0); PG8_BAR; PG8_MMA(0, 0, At, B0); PG8_MMA(0, 1, At, B1); PG8_BAR; PG8_SCHED;
;             PG8_LDA(At, 0, 1); PG8_STAGE(PG8_SB(0, 0), b2, voffB); PG8_STAGE(PG8_SB(0, 1), b2 + hstep, voffB); PG8_STAGE(PG8_SA(0, 0), a2, voffA);
;             PG8_WAIT_V(8); PG8_WAIT_L(0); PG8_BAR; PG8_MMA(1, 0, At, B0); PG8_MMA(1, 1, At, B1); PG8_BAR; PG8_SCHED;
;             PG8_LDB(B0, 1, 0); PG8_LDB(B1, 1, 1); PG8_SCHED; PG8_LDA(At, 1, 0); PG8_STAGE(PG8_SA(0, 1), a2 + hstep, voffA);
;             PG8_WAIT_V(8); PG8_WAIT_L(0); PG8_BAR; PG8_MMA(0, 0, At, B0); PG8_MMA(0, 1, At, B1); PG8_BAR; PG8_SCHED;
;             PG8_LDA(At, 1, 1); PG8_STAGE(PG8_SB(1, 0), b3, voffB); PG8_STAGE(PG8_SB(1, 1), b3 + hstep, voffB); PG8_STAGE(PG8_SA(1, 0), a3, voffA);
;             PG8_WAIT_V(8); PG8_WAIT_L(0); PG8_BAR; PG8_MMA(1, 0, At, B0); PG8_MMA(1, 1, At, B1); PG8_BAR; PG8_SCHED;
	s_waitcnt lgkmcnt(0)
	v_mfma_f32_16x16x32_bf16 v[128:131], v[132:135], v[200:203], v[128:131]
	v_mfma_f32_16x16x32_bf16 v[124:127], v[140:143], v[200:203], v[124:127]
	v_mfma_f32_16x16x32_bf16 v[112:115], v[132:135], v[208:211], v[112:115]
	v_mfma_f32_16x16x32_bf16 v[108:111], v[140:143], v[208:211], v[108:111]
	v_mfma_f32_16x16x32_bf16 v[96:99], v[132:135], v[216:219], v[96:99]
	v_mfma_f32_16x16x32_bf16 v[92:95], v[140:143], v[216:219], v[92:95]
	v_mfma_f32_16x16x32_bf16 v[80:83], v[132:135], v[224:227], v[80:83]
	v_mfma_f32_16x16x32_bf16 v[76:79], v[140:143], v[224:227], v[76:79]
	v_mfma_f32_16x16x32_bf16 v[128:131], v[136:139], v[204:207], v[128:131]
	v_mfma_f32_16x16x32_bf16 v[124:127], v[174:177], v[204:207], v[124:127]
	v_mfma_f32_16x16x32_bf16 v[112:115], v[136:139], v[212:215], v[112:115]
	v_mfma_f32_16x16x32_bf16 v[108:111], v[174:177], v[212:215], v[108:111]
	v_mfma_f32_16x16x32_bf16 v[96:99], v[136:139], v[220:223], v[96:99]
	v_mfma_f32_16x16x32_bf16 v[92:95], v[174:177], v[220:223], v[92:95]
	v_mfma_f32_16x16x32_bf16 v[80:83], v[136:139], v[238:241], v[80:83]
	v_mfma_f32_16x16x32_bf16 v[76:79], v[174:177], v[238:241], v[76:79]
	v_mfma_f32_16x16x32_bf16 v[120:123], v[178:181], v[200:203], v[120:123]
	v_mfma_f32_16x16x32_bf16 v[116:119], v[192:195], v[200:203], v[116:119]
	v_mfma_f32_16x16x32_bf16 v[104:107], v[178:181], v[208:211], v[104:107]
	v_mfma_f32_16x16x32_bf16 v[100:103], v[192:195], v[208:211], v[100:103]
	v_mfma_f32_16x16x32_bf16 v[88:91], v[178:181], v[216:219], v[88:91]
	v_mfma_f32_16x16x32_bf16 v[84:87], v[192:195], v[216:219], v[84:87]
	v_mfma_f32_16x16x32_bf16 v[72:75], v[178:181], v[224:227], v[72:75]
	v_mfma_f32_16x16x32_bf16 v[68:71], v[192:195], v[224:227], v[68:71]
	v_mfma_f32_16x16x32_bf16 v[120:123], v[188:191], v[204:207], v[120:123]
	v_mfma_f32_16x16x32_bf16 v[116:119], v[196:199], v[204:207], v[116:119]
	v_mfma_f32_16x16x32_bf16 v[104:107], v[188:191], v[212:215], v[104:107]
	v_mfma_f32_16x16x32_bf16 v[100:103], v[196:199], v[212:215], v[100:103]
	v_mfma_f32_16x16x32_bf16 v[88:91], v[188:191], v[220:223], v[88:91]
	v_mfma_f32_16x16x32_bf16 v[84:87], v[196:199], v[220:223], v[84:87]
	v_mfma_f32_16x16x32_bf16 v[72:75], v[188:191], v[238:241], v[72:75]
	v_mfma_f32_16x16x32_bf16 v[68:71], v[196:199], v[238:241], v[68:71]
	s_barrier
	s_add_i32 s58, s81, s61
	v_lshl_add_u64 v[144:145], v[144:145], 0, s[0:1]
	s_mov_b32 m0, s58
	ds_read_b128 v[200:203], v186 offset:49152
	ds_read_b128 v[204:207], v186 offset:50176
	ds_read_b128 v[208:211], v186 offset:51200
	ds_read_b128 v[212:215], v186 offset:52224
	ds_read_b128 v[216:219], v186 offset:53248
	ds_read_b128 v[220:223], v186 offset:54272
	ds_read_b128 v[224:227], v186 offset:55296
	ds_read_b128 v[238:241], v186 offset:56320
	global_load_lds_dwordx4 v[144:145], off
	v_lshl_add_u64 v[144:145], v[242:243], 0, s[0:1]
	s_add_i32 m0, s58, 0x2000
	s_add_i32 s58, s82, s61
	global_load_lds_dwordx4 v[144:145], off
	v_lshl_add_u64 v[144:145], v[244:245], 0, s[0:1]
	s_mov_b32 m0, s58
	s_nop 0
	global_load_lds_dwordx4 v[144:145], off
	v_lshl_add_u64 v[144:145], v[246:247], 0, s[0:1]
	s_add_i32 m0, s58, 0x2000
	s_nop 0
	global_load_lds_dwordx4 v[144:145], off
	v_lshl_add_u64 v[144:145], v[248:249], 0, s[0:1]
	s_mov_b32 m0, s66
	s_nop 0
	global_load_lds_dwordx4 v[144:145], off
	v_lshl_add_u64 v[144:145], v[148:149], 0, s[0:1]
	s_mov_b32 m0, s67
	s_nop 0
	global_load_lds_dwordx4 v[144:145], off
	s_waitcnt vmcnt(8)
	s_waitcnt lgkmcnt(0)
	s_barrier
	s_waitcnt lgkmcnt(0)
	v_mfma_f32_16x16x32_bf16 v[64:67], v[132:135], v[200:203], v[64:67]
	v_mfma_f32_16x16x32_bf16 v[60:63], v[140:143], v[200:203], v[60:63]
	v_mfma_f32_16x16x32_bf16 v[48:51], v[132:135], v[208:211], v[48:51]
	v_mfma_f32_16x16x32_bf16 v[44:47], v[140:143], v[208:211], v[44:47]
	v_mfma_f32_16x16x32_bf16 v[32:35], v[132:135], v[216:219], v[32:35]
	v_mfma_f32_16x16x32_bf16 v[28:31], v[140:143], v[216:219], v[28:31]
	v_mfma_f32_16x16x32_bf16 v[16:19], v[132:135], v[224:227], v[16:19]
	v_mfma_f32_16x16x32_bf16 v[12:15], v[140:143], v[224:227], v[12:15]
	v_mfma_f32_16x16x32_bf16 v[64:67], v[136:139], v[204:207], v[64:67]
	v_mfma_f32_16x16x32_bf16 v[60:63], v[174:177], v[204:207], v[60:63]
	v_mfma_f32_16x16x32_bf16 v[48:51], v[136:139], v[212:215], v[48:51]
	v_mfma_f32_16x16x32_bf16 v[44:47], v[174:177], v[212:215], v[44:47]
	v_mfma_f32_16x16x32_bf16 v[32:35], v[136:139], v[220:223], v[32:35]
	v_mfma_f32_16x16x32_bf16 v[28:31], v[174:177], v[220:223], v[28:31]
	v_mfma_f32_16x16x32_bf16 v[16:19], v[136:139], v[238:241], v[16:19]
	v_mfma_f32_16x16x32_bf16 v[12:15], v[174:177], v[238:241], v[12:15]
	v_mfma_f32_16x16x32_bf16 v[56:59], v[178:181], v[200:203], v[56:59]
	v_mfma_f32_16x16x32_bf16 v[52:55], v[192:195], v[200:203], v[52:55]
	v_mfma_f32_16x16x32_bf16 v[40:43], v[178:181], v[208:211], v[40:43]
	v_mfma_f32_16x16x32_bf16 v[36:39], v[192:195], v[208:211], v[36:39]
	v_mfma_f32_16x16x32_bf16 v[24:27], v[178:181], v[216:219], v[24:27]
	v_mfma_f32_16x16x32_bf16 v[20:23], v[192:195], v[216:219], v[20:23]
	v_mfma_f32_16x16x32_bf16 v[8:11], v[178:181], v[224:227], v[8:11]
	v_mfma_f32_16x16x32_bf16 v[4:7], v[192:195], v[224:227], v[4:7]
	v_mfma_f32_16x16x32_bf16 v[56:59], v[188:191], v[204:207], v[56:59]
	v_mfma_f32_16x16x32_bf16 v[52:55], v[196:199], v[204:207], v[52:55]
	v_mfma_f32_16x16x32_bf16 v[40:43], v[188:191], v[212:215], v[40:43]
	v_mfma_f32_16x16x32_bf16 v[36:39], v[196:199], v[212:215], v[36:39]
	v_mfma_f32_16x16x32_bf16 v[24:27], v[188:191], v[220:223], v[24:27]
	v_mfma_f32_16x16x32_bf16 v[20:23], v[196:199], v[220:223], v[20:23]
	v_mfma_f32_16x16x32_bf16 v[8:11], v[188:191], v[238:241], v[8:11]
	v_mfma_f32_16x16x32_bf16 v[4:7], v[196:199], v[238:241], v[4:7]
	s_barrier
	s_add_u32 s6, s6, 0x100
	s_addc_u32 s7, s7, 0
	s_add_u32 s78, s78, 0x100
	s_addc_u32 s79, s79, 0
	s_cmp_ge_u32 s80, s69
	s_mov_b32 s58, s80
	s_cbranch_scc0 .LBB0_476
	s_setprio 0
	s_and_b64 vcc, exec, s[50:51]
	s_cbranch_vccz .LBB0_479
	s_barrier

; template <class Epi, class Sched, bool ALIGN_EPI = false, bool SP2 = false>
; __device__ __forceinline__ void gemm_phase(PG8_LAS unsigned char* lds, const Gemm g, const Sched& S, const Epi& E, const int tid) {
;     ...
;         const bool has_next = S.next(ui + 1, nxt);
;         const char* nA = has_next ? (const char*)g.A + (size_t)nxt.pm * tstep : cA; const char* nB = has_next ? (const char*)g.Bt + (size_t)nxt.pn * tstep : cB;
;     ...
; #pragma unroll
;         for (int a = 0; a < 2; ++a)
; #pragma unroll
;             for (int b = 0; b < 2; ++b)
; #pragma unroll
;                 for (int m = 0; m < 4; ++m)
; #pragma unroll
;                     for (int n = 0; n < 2; ++n) acc[a][b][m][n] = (f32x4){0.f, 0.f, 0.f, 0.f};
;         cur = nxt; cA = nA; cB = nB; ++ui;
.LBB0_521:
	s_ashr_i32 s13, s12, 31
	s_lshl_b64 s[14:15], s[12:13], 19
	s_add_u32 s14, s26, s14
	s_addc_u32 s15, s27, s15
	s_and_b64 s[16:17], s[2:3], exec
	s_cselect_b32 s13, s15, s19
	s_cselect_b32 s47, s14, s18
	s_ashr_i32 s11, s10, 31
	s_lshl_b64 s[16:17], s[10:11], 19
	s_add_u32 s16, s34, s16
	s_addc_u32 s17, s36, s17
	s_and_b64 s[22:23], s[2:3], exec
	s_cselect_b32 s11, s17, s21
	s_cselect_b32 s48, s16, s20
	s_add_u32 s18, s18, 0x40080
	s_addc_u32 s19, s19, 0
	s_add_u32 s49, s20, 0x100
	v_mov_b32_e32 v4, 0
	s_addc_u32 s50, s21, 0
	s_mov_b32 s51, -2
	v_mov_b64_e32 v[4:5], 0
	v_mov_b64_e32 v[6:7], 0
	v_mov_b64_e32 v[8:9], 0
	v_mov_b64_e32 v[10:11], 0
	v_mov_b64_e32 v[12:13], 0
	v_mov_b64_e32 v[14:15], 0
	v_mov_b64_e32 v[16:17], 0
	v_mov_b64_e32 v[18:19], 0
	v_mov_b64_e32 v[20:21], 0
	v_mov_b64_e32 v[22:23], 0
	v_mov_b64_e32 v[24:25], 0
	v_mov_b64_e32 v[26:27], 0
	v_mov_b64_e32 v[28:29], 0
	v_mov_b64_e32 v[30:31], 0
	v_mov_b64_e32 v[32:33], 0
	v_mov_b64_e32 v[34:35], 0
	v_mov_b64_e32 v[36:37], 0
	v_mov_b64_e32 v[38:39], 0
	v_mov_b64_e32 v[40:41], 0
	v_mov_b64_e32 v[42:43], 0
	v_mov_b64_e32 v[44:45], 0
	v_mov_b64_e32 v[46:47], 0
	v_mov_b64_e32 v[48:49], 0
	v_mov_b64_e32 v[50:51], 0
	v_mov_b64_e32 v[52:53], 0
	v_mov_b64_e32 v[54:55], 0
	v_mov_b64_e32 v[56:57], 0
	v_mov_b64_e32 v[58:59], 0
	v_mov_b64_e32 v[60:61], 0
	v_mov_b64_e32 v[62:63], 0
	v_mov_b64_e32 v[64:65], 0
	v_mov_b64_e32 v[66:67], 0
	v_mov_b64_e32 v[68:69], 0
	v_mov_b64_e32 v[70:71], 0
	v_mov_b64_e32 v[72:73], 0
	v_mov_b64_e32 v[74:75], 0
	v_mov_b64_e32 v[76:77], 0
	v_mov_b64_e32 v[78:79], 0
	v_mov_b64_e32 v[80:81], 0
	v_mov_b64_e32 v[82:83], 0
	v_mov_b64_e32 v[84:85], 0
	v_mov_b64_e32 v[86:87], 0
	v_mov_b64_e32 v[88:89], 0
	v_mov_b64_e32 v[90:91], 0
	v_mov_b64_e32 v[92:93], 0
	v_mov_b64_e32 v[94:95], 0
	v_mov_b64_e32 v[96:97], 0
	v_mov_b64_e32 v[98:99], 0
	v_mov_b64_e32 v[100:101], 0
	v_mov_b64_e32 v[102:103], 0
	v_mov_b64_e32 v[104:105], 0
	v_mov_b64_e32 v[106:107], 0
	v_mov_b64_e32 v[108:109], 0
	v_mov_b64_e32 v[110:111], 0
	v_mov_b64_e32 v[112:113], 0
	v_mov_b64_e32 v[114:115], 0
	v_mov_b64_e32 v[116:117], 0
	v_mov_b64_e32 v[118:119], 0
	v_mov_b64_e32 v[120:121], 0
	v_mov_b64_e32 v[122:123], 0
	v_mov_b64_e32 v[124:125], 0
	v_mov_b64_e32 v[126:127], 0
	v_mov_b64_e32 v[128:129], 0
	v_mov_b64_e32 v[130:131], 0
	s_cmp_lt_u32 s92, 4
	s_cbranch_scc1 .Lprio_skip3
	s_setprio 1
.Lprio_skip3:
.LBB0_522:
	s_add_u32 s20, s18, 0xfffc0080
	s_addc_u32 s21, s19, -1
	s_add_i32 s52, 0, 0x10000
	s_cmp_eq_u32 s51, 12
	s_cselect_b32 s23, s13, s21
	s_cselect_b32 s22, s47, s20
	v_add_u32_e32 v148, s52, v146
	s_cselect_b32 s21, s11, s50
	s_cselect_b32 s20, s48, s49
	s_add_i32 s54, 0, 0x14000
	ds_read_b128 v[142:145], v148
	ds_read_b128 v[166:169], v148 offset:1024
	ds_read_b128 v[170:173], v148 offset:2048
	ds_read_b128 v[174:177], v148 offset:3072
	v_add_u32_e32 v148, s54, v146
	ds_read_b128 v[178:181], v148
	ds_read_b128 v[182:185], v148 offset:1024
	ds_read_b128 v[186:189], v148 offset:2048
	ds_read_b128 v[190:193], v148 offset:3072
	v_lshl_add_u64 v[226:227], s[18:19], 0, v[138:139]
	s_add_i32 m0, s38, 0xc000
	ds_read_b128 v[194:197], v153
	ds_read_b128 v[198:201], v153 offset:1024
	ds_read_b128 v[202:205], v153 offset:2048
	ds_read_b128 v[206:209], v153 offset:3072
	ds_read_b128 v[210:213], v153 offset:4096
	ds_read_b128 v[214:217], v153 offset:5120
	ds_read_b128 v[218:221], v153 offset:6144
	ds_read_b128 v[222:225], v153 offset:7168
	global_load_lds_dwordx4 v[226:227], off
	v_lshl_add_u64 v[226:227], s[18:19], 0, v[140:141]
	s_add_i32 m0, s38, 0xe000
	s_nop 0
	global_load_lds_dwordx4 v[226:227], off
	s_waitcnt vmcnt(8)
	s_waitcnt lgkmcnt(0)
	s_barrier
	s_waitcnt lgkmcnt(0)
	v_mfma_f32_16x16x32_bf16 v[128:131], v[142:145], v[194:197], v[128:131]
	v_mfma_f32_16x16x32_bf16 v[120:123], v[170:173], v[194:197], v[120:123]
	v_mfma_f32_16x16x32_bf16 v[112:115], v[142:145], v[202:205], v[112:115]
	v_mfma_f32_16x16x32_bf16 v[104:107], v[170:173], v[202:205], v[104:107]
	v_mfma_f32_16x16x32_bf16 v[96:99], v[142:145], v[210:213], v[96:99]
	v_mfma_f32_16x16x32_bf16 v[88:91], v[170:173], v[210:213], v[88:91]
	v_mfma_f32_16x16x32_bf16 v[80:83], v[142:145], v[218:221], v[80:83]
	v_mfma_f32_16x16x32_bf16 v[72:75], v[170:173], v[218:221], v[72:75]
	v_mfma_f32_16x16x32_bf16 v[128:131], v[166:169], v[198:201], v[128:131]
	v_mfma_f32_16x16x32_bf16 v[120:123], v[174:177], v[198:201], v[120:123]
	v_mfma_f32_16x16x32_bf16 v[112:115], v[166:169], v[206:209], v[112:115]
	v_mfma_f32_16x16x32_bf16 v[104:107], v[174:177], v[206:209], v[104:107]
	v_mfma_f32_16x16x32_bf16 v[96:99], v[166:169], v[214:217], v[96:99]
	v_mfma_f32_16x16x32_bf16 v[88:91], v[174:177], v[214:217], v[88:91]
	v_mfma_f32_16x16x32_bf16 v[80:83], v[166:169], v[222:225], v[80:83]
	v_mfma_f32_16x16x32_bf16 v[72:75], v[174:177], v[222:225], v[72:75]
	v_mfma_f32_16x16x32_bf16 v[124:127], v[178:181], v[194:197], v[124:127]
	v_mfma_f32_16x16x32_bf16 v[116:119], v[186:189], v[194:197], v[116:119]
	v_mfma_f32_16x16x32_bf16 v[108:111], v[178:181], v[202:205], v[108:111]
	v_mfma_f32_16x16x32_bf16 v[100:103], v[186:189], v[202:205], v[100:103]
	v_mfma_f32_16x16x32_bf16 v[92:95], v[178:181], v[210:213], v[92:95]
	v_mfma_f32_16x16x32_bf16 v[84:87], v[186:189], v[210:213], v[84:87]
	v_mfma_f32_16x16x32_bf16 v[76:79], v[178:181], v[218:221], v[76:79]
	v_mfma_f32_16x16x32_bf16 v[68:71], v[186:189], v[218:221], v[68:71]
	v_mfma_f32_16x16x32_bf16 v[124:127], v[182:185], v[198:201], v[124:127]
	v_mfma_f32_16x16x32_bf16 v[116:119], v[190:193], v[198:201], v[116:119]
	v_mfma_f32_16x16x32_bf16 v[108:111], v[182:185], v[206:209], v[108:111]
	v_mfma_f32_16x16x32_bf16 v[100:103], v[190:193], v[206:209], v[100:103]
	v_mfma_f32_16x16x32_bf16 v[92:95], v[182:185], v[214:217], v[92:95]
	v_mfma_f32_16x16x32_bf16 v[84:87], v[190:193], v[214:217], v[84:87]
	v_mfma_f32_16x16x32_bf16 v[76:79], v[182:185], v[222:225], v[76:79]
	v_mfma_f32_16x16x32_bf16 v[68:71], v[190:193], v[222:225], v[68:71]
	s_barrier
; #define PG8_STAGE(bufoff, gbase, voff) do { _Pragma("unroll") for (int _i = 0; _i < 2; ++_i) \
;         __builtin_amdgcn_global_load_lds((const unsigned*)((const char*)(gbase) + (voff)[_i]), (PG8_LAS unsigned*)(lds + (bufoff) + ldsw + _i * 8192), 16, 0, 0); } while (0)
; #define PG8_LDA(dst, b, h) do { _Pragma("unroll") for (int m = 0; m < 4; ++m) _Pragma("unroll") for (int k = 0; k < 2; ++k) dst[m][k] = *(const PG8_LAS bf16x8*)(lds + PG8_SA(b, h) + aoff + m * 2048 + k * 1024); } while (0)
; #define PG8_LDB(dst, b, h) do { _Pragma("unroll") for (int n = 0; n < 2; ++n) _Pragma("unroll") for (int k = 0; k < 2; ++k) dst[n][k] = *(const PG8_LAS bf16x8*)(lds + PG8_SB(b, h) + boff + n * 2048 + k * 1024); } while (0)
; #define PG8_MMA(ai, bj, At, Bt) do { __builtin_amdgcn_s_setprio(1); _Pragma("unroll") for (int m = 0; m < 4; ++m) _Pragma("unroll") for (int n = 0; n < 2; ++n) _Pragma("unroll") for (int k = 0; k < 2; ++k) \
;         acc[ai][bj][m][n] = __builtin_amdgcn_mfma_f32_16x16x32_bf16(Bt[n][k], At[m][k], acc[ai][bj][m][n], 0, 0, 0); __builtin_amdgcn_s_setprio(0); } while (0)
; #define PG8_WAIT_V(n) asm volatile("s_waitcnt vmcnt(" #n ")" ::: "memory")
; #define PG8_WAIT_L(n) asm volatile("s_waitcnt lgkmcnt(" #n ")" ::: "memory")
; #define PG8_BAR __builtin_amdgcn_s_barrier()
; #define PG8_SCHED __builtin_amdgcn_sched_barrier(0)
; template <class Epi, class Sched, bool ALIGN_EPI = false, bool SP2 = false>
; __device__ __forceinline__ void gemm_phase(PG8_LAS unsigned char* lds, const Gemm g, const Sched& S, const Epi& E, const int tid) {
;     ...
;             PG8_WAIT_V(8); PG8_WAIT_L(0); PG8_BAR; PG8_MMA(0, 0, At, B0); PG8_MMA(0, 1, At, B1); PG8_BAR; PG8_SCHED;
;             PG8_LDA(At, 0, 1); PG8_STAGE(PG8_SB(0, 0), b2, voffB); PG8_STAGE(PG8_SB(0, 1), b2 + hstep, voffB); PG8_STAGE(PG8_SA(0, 0), a2, voffA);
;             PG8_WAIT_V(8); PG8_WAIT_L(0); PG8_BAR; PG8_MMA(1, 0, At, B0); PG8_MMA(1, 1, At, B1); PG8_BAR; PG8_SCHED;
;             PG8_LDB(B0, 1, 0); PG8_LDB(B1, 1, 1); PG8_SCHED; PG8_LDA(At, 1, 0); PG8_STAGE(PG8_SA(0, 1), a2 + hstep, voffA);
;             PG8_WAIT_V(8); PG8_WAIT_L(0); PG8_BAR; PG8_MMA(0, 0, At, B0); PG8_MMA(0, 1, At, B1); PG8_BAR; PG8_SCHED;
	s_add_i32 s52, s52, s37
	v_lshl_add_u64 v[226:227], s[20:21], 0, v[134:135]
	s_mov_b32 m0, s52
	ds_read_b128 v[194:197], v153 offset:16384
	ds_read_b128 v[198:201], v153 offset:17408
	ds_read_b128 v[202:205], v153 offset:18432
	ds_read_b128 v[206:209], v153 offset:19456
	ds_read_b128 v[210:213], v153 offset:20480
	ds_read_b128 v[214:217], v153 offset:21504
	ds_read_b128 v[218:221], v153 offset:22528
	ds_read_b128 v[222:225], v153 offset:23552
	global_load_lds_dwordx4 v[226:227], off
	s_add_i32 m0, s52, 0x2000
	s_add_u32 s52, s20, 0x40000
	v_lshl_add_u64 v[238:239], s[20:21], 0, v[0:1]
	s_addc_u32 s53, s21, 0
	s_add_i32 s54, s54, s37
	global_load_lds_dwordx4 v[238:239], off
	v_lshl_add_u64 v[240:241], s[52:53], 0, v[134:135]
	s_mov_b32 m0, s54
	v_lshl_add_u64 v[242:243], s[22:23], 0, v[132:133]
	global_load_lds_dwordx4 v[240:241], off
	v_lshl_add_u64 v[240:241], s[52:53], 0, v[0:1]
	s_add_i32 m0, s54, 0x2000
	s_nop 0
	global_load_lds_dwordx4 v[240:241], off
	v_lshl_add_u64 v[240:241], s[22:23], 0, v[136:137]
	s_mov_b32 m0, s38
	s_nop 0
	global_load_lds_dwordx4 v[240:241], off
	s_mov_b32 m0, s39
	s_nop 0
	global_load_lds_dwordx4 v[242:243], off
	s_waitcnt vmcnt(8)
	s_waitcnt lgkmcnt(0)
	s_barrier
	s_waitcnt lgkmcnt(0)
	v_mfma_f32_16x16x32_bf16 v[64:67], v[142:145], v[194:197], v[64:67]
	v_mfma_f32_16x16x32_bf16 v[56:59], v[170:173], v[194:197], v[56:59]
	v_mfma_f32_16x16x32_bf16 v[48:51], v[142:145], v[202:205], v[48:51]
	v_mfma_f32_16x16x32_bf16 v[40:43], v[170:173], v[202:205], v[40:43]
	v_mfma_f32_16x16x32_bf16 v[32:35], v[142:145], v[210:213], v[32:35]
	v_mfma_f32_16x16x32_bf16 v[24:27], v[170:173], v[210:213], v[24:27]
	v_mfma_f32_16x16x32_bf16 v[16:19], v[142:145], v[218:221], v[16:19]
	v_mfma_f32_16x16x32_bf16 v[8:11], v[170:173], v[218:221], v[8:11]
	v_mfma_f32_16x16x32_bf16 v[64:67], v[166:169], v[198:201], v[64:67]
	v_mfma_f32_16x16x32_bf16 v[56:59], v[174:177], v[198:201], v[56:59]
	v_mfma_f32_16x16x32_bf16 v[48:51], v[166:169], v[206:209], v[48:51]
	v_mfma_f32_16x16x32_bf16 v[40:43], v[174:177], v[206:209], v[40:43]
	v_mfma_f32_16x16x32_bf16 v[32:35], v[166:169], v[214:217], v[32:35]
	v_mfma_f32_16x16x32_bf16 v[24:27], v[174:177], v[214:217], v[24:27]
	v_mfma_f32_16x16x32_bf16 v[16:19], v[166:169], v[222:225], v[16:19]
	v_mfma_f32_16x16x32_bf16 v[8:11], v[174:177], v[222:225], v[8:11]
	v_mfma_f32_16x16x32_bf16 v[60:63], v[178:181], v[194:197], v[60:63]
	v_mfma_f32_16x16x32_bf16 v[52:55], v[186:189], v[194:197], v[52:55]
	v_mfma_f32_16x16x32_bf16 v[44:47], v[178:181], v[202:205], v[44:47]
	v_mfma_f32_16x16x32_bf16 v[36:39], v[186:189], v[202:205], v[36:39]
	v_mfma_f32_16x16x32_bf16 v[28:31], v[178:181], v[210:213], v[28:31]
	v_mfma_f32_16x16x32_bf16 v[20:23], v[186:189], v[210:213], v[20:23]
	v_mfma_f32_16x16x32_bf16 v[12:15], v[178:181], v[218:221], v[12:15]
	v_mfma_f32_16x16x32_bf16 v[4:7], v[186:189], v[218:221], v[4:7]
	v_mfma_f32_16x16x32_bf16 v[60:63], v[182:185], v[198:201], v[60:63]
	v_mfma_f32_16x16x32_bf16 v[52:55], v[190:193], v[198:201], v[52:55]
	v_mfma_f32_16x16x32_bf16 v[44:47], v[182:185], v[206:209], v[44:47]
	v_mfma_f32_16x16x32_bf16 v[36:39], v[190:193], v[206:209], v[36:39]
	v_mfma_f32_16x16x32_bf16 v[28:31], v[182:185], v[214:217], v[28:31]
	v_mfma_f32_16x16x32_bf16 v[20:23], v[190:193], v[214:217], v[20:23]
	v_mfma_f32_16x16x32_bf16 v[12:15], v[182:185], v[222:225], v[12:15]
	v_mfma_f32_16x16x32_bf16 v[4:7], v[190:193], v[222:225], v[4:7]
	s_barrier
	s_add_i32 s52, 0, 0x18000
	v_add_u32_e32 v148, s52, v146
	s_add_i32 s53, 0, 0x1c000
	ds_read_b128 v[142:145], v148
	ds_read_b128 v[166:169], v148 offset:1024
	ds_read_b128 v[170:173], v148 offset:2048
	ds_read_b128 v[174:177], v148 offset:3072
	v_add_u32_e32 v148, s53, v146
	ds_read_b128 v[178:181], v148
	ds_read_b128 v[182:185], v148 offset:1024
	ds_read_b128 v[186:189], v148 offset:2048
	ds_read_b128 v[190:193], v148 offset:3072
	s_add_u32 s22, s22, 0x40000
	s_addc_u32 s23, s23, 0
	s_mov_b32 m0, s40
	v_lshl_add_u64 v[244:245], s[22:23], 0, v[136:137]
	ds_read_b128 v[194:197], v153 offset:32768
	ds_read_b128 v[198:201], v153 offset:33792
	ds_read_b128 v[202:205], v153 offset:34816
	ds_read_b128 v[206:209], v153 offset:35840
	ds_read_b128 v[210:213], v153 offset:36864
	ds_read_b128 v[214:217], v153 offset:37888
	ds_read_b128 v[218:221], v153 offset:38912
	ds_read_b128 v[222:225], v153 offset:39936
	global_load_lds_dwordx4 v[244:245], off
	v_lshl_add_u64 v[244:245], s[22:23], 0, v[132:133]
	s_mov_b32 m0, s41
	s_nop 0
	global_load_lds_dwordx4 v[244:245], off
	s_waitcnt vmcnt(8)
	s_waitcnt lgkmcnt(0)
	s_barrier
; #define PG8_STAGE(bufoff, gbase, voff) do { _Pragma("unroll") for (int _i = 0; _i < 2; ++_i) \
;         __builtin_amdgcn_global_load_lds((const unsigned*)((const char*)(gbase) + (voff)[_i]), (PG8_LAS unsigned*)(lds + (bufoff) + ldsw + _i * 8192), 16, 0, 0); } while (0)
; #define PG8_LDA(dst, b, h) do { _Pragma("unroll") for (int m = 0; m < 4; ++m) _Pragma("unroll") for (int k = 0; k < 2; ++k) dst[m][k] = *(const PG8_LAS bf16x8*)(lds + PG8_SA(b, h) + aoff + m * 2048 + k * 1024); } while (0)
; #define PG8_LDB(dst, b, h) do { _Pragma("unroll") for (int n = 0; n < 2; ++n) _Pragma("unroll") for (int k = 0; k < 2; ++k) dst[n][k] = *(const PG8_LAS bf16x8*)(lds + PG8_SB(b, h) + boff + n * 2048 + k * 1024); } while (0)
; #define PG8_MMA(ai, bj, At, Bt) do { __builtin_amdgcn_s_setprio(1); _Pragma("unroll") for (int m = 0; m < 4; ++m) _Pragma("unroll") for (int n = 0; n < 2; ++n) _Pragma("unroll") for (int k = 0; k < 2; ++k) \
;         acc[ai][bj][m][n] = __builtin_amdgcn_mfma_f32_16x16x32_bf16(Bt[n][k], At[m][k], acc[ai][bj][m][n], 0, 0, 0); __builtin_amdgcn_s_setprio(0); } while (0)
; #define PG8_WAIT_V(n) asm volatile("s_waitcnt vmcnt(" #n ")" ::: "memory")
; #define PG8_WAIT_L(n) asm volatile("s_waitcnt lgkmcnt(" #n ")" ::: "memory")
; template <class Epi, class Sched, bool ALIGN_EPI = false, bool SP2 = false>
; __device__ __forceinline__ void gemm_phase(PG8_LAS unsigned char* lds, const Gemm g, const Sched& S, const Epi& E, const int tid) {
;     ...
;             PG8_WAIT_V(8); PG8_WAIT_L(0); PG8_BAR; PG8_MMA(0, 0, At, B0); PG8_MMA(0, 1, At, B1); PG8_BAR; PG8_SCHED;
;             PG8_LDA(At, 0, 1); PG8_STAGE(PG8_SB(0, 0), b2, voffB); PG8_STAGE(PG8_SB(0, 1), b2 + hstep, voffB); PG8_STAGE(PG8_SA(0, 0), a2, voffA);
;             PG8_WAIT_V(8); PG8_WAIT_L(0); PG8_BAR; PG8_MMA(1, 0, At, B0); PG8_MMA(1, 1, At, B1); PG8_BAR; PG8_SCHED;
;             PG8_LDB(B0, 1, 0); PG8_LDB(B1, 1, 1); PG8_SCHED; PG8_LDA(At, 1, 0); PG8_STAGE(PG8_SA(0, 1), a2 + hstep, voffA);
;             PG8_WAIT_V(8); PG8_WAIT_L(0); PG8_BAR; PG8_MMA(0, 0, At, B0); PG8_MMA(0, 1, At, B1); PG8_BAR; PG8_SCHED;
;             PG8_LDA(At, 1, 1); PG8_STAGE(PG8_SB(1, 0), b3, voffB); PG8_STAGE(PG8_SB(1, 1), b3 + hstep, voffB); PG8_STAGE(PG8_SA(1, 0), a3, voffA);
;             PG8_WAIT_V(8); PG8_WAIT_L(0); PG8_BAR; PG8_MMA(1, 0, At, B0); PG8_MMA(1, 1, At, B1); PG8_BAR; PG8_SCHED;
	s_waitcnt lgkmcnt(0)
	v_mfma_f32_16x16x32_bf16 v[128:131], v[142:145], v[194:197], v[128:131]
	v_mfma_f32_16x16x32_bf16 v[120:123], v[170:173], v[194:197], v[120:123]
	v_mfma_f32_16x16x32_bf16 v[112:115], v[142:145], v[202:205], v[112:115]
	v_mfma_f32_16x16x32_bf16 v[104:107], v[170:173], v[202:205], v[104:107]
	v_mfma_f32_16x16x32_bf16 v[96:99], v[142:145], v[210:213], v[96:99]
	v_mfma_f32_16x16x32_bf16 v[88:91], v[170:173], v[210:213], v[88:91]
	v_mfma_f32_16x16x32_bf16 v[80:83], v[142:145], v[218:221], v[80:83]
	v_mfma_f32_16x16x32_bf16 v[72:75], v[170:173], v[218:221], v[72:75]
	v_mfma_f32_16x16x32_bf16 v[128:131], v[166:169], v[198:201], v[128:131]
	v_mfma_f32_16x16x32_bf16 v[120:123], v[174:177], v[198:201], v[120:123]
	v_mfma_f32_16x16x32_bf16 v[112:115], v[166:169], v[206:209], v[112:115]
	v_mfma_f32_16x16x32_bf16 v[104:107], v[174:177], v[206:209], v[104:107]
	v_mfma_f32_16x16x32_bf16 v[96:99], v[166:169], v[214:217], v[96:99]
	v_mfma_f32_16x16x32_bf16 v[88:91], v[174:177], v[214:217], v[88:91]
	v_mfma_f32_16x16x32_bf16 v[80:83], v[166:169], v[222:225], v[80:83]
	v_mfma_f32_16x16x32_bf16 v[72:75], v[174:177], v[222:225], v[72:75]
	v_mfma_f32_16x16x32_bf16 v[124:127], v[178:181], v[194:197], v[124:127]
	v_mfma_f32_16x16x32_bf16 v[116:119], v[186:189], v[194:197], v[116:119]
	v_mfma_f32_16x16x32_bf16 v[108:111], v[178:181], v[202:205], v[108:111]
	v_mfma_f32_16x16x32_bf16 v[100:103], v[186:189], v[202:205], v[100:103]
	v_mfma_f32_16x16x32_bf16 v[92:95], v[178:181], v[210:213], v[92:95]
	v_mfma_f32_16x16x32_bf16 v[84:87], v[186:189], v[210:213], v[84:87]
	v_mfma_f32_16x16x32_bf16 v[76:79], v[178:181], v[218:221], v[76:79]
	v_mfma_f32_16x16x32_bf16 v[68:71], v[186:189], v[218:221], v[68:71]
	v_mfma_f32_16x16x32_bf16 v[124:127], v[182:185], v[198:201], v[124:127]
	v_mfma_f32_16x16x32_bf16 v[116:119], v[190:193], v[198:201], v[116:119]
	v_mfma_f32_16x16x32_bf16 v[108:111], v[182:185], v[206:209], v[108:111]
	v_mfma_f32_16x16x32_bf16 v[100:103], v[190:193], v[206:209], v[100:103]
	v_mfma_f32_16x16x32_bf16 v[92:95], v[182:185], v[214:217], v[92:95]
	v_mfma_f32_16x16x32_bf16 v[84:87], v[190:193], v[214:217], v[84:87]
	v_mfma_f32_16x16x32_bf16 v[76:79], v[182:185], v[222:225], v[76:79]
	v_mfma_f32_16x16x32_bf16 v[68:71], v[190:193], v[222:225], v[68:71]
	s_barrier
	s_add_i32 s22, s52, s37
	v_lshl_add_u64 v[226:227], v[226:227], 0, s[0:1]
	s_mov_b32 m0, s22
	ds_read_b128 v[194:197], v153 offset:49152
	ds_read_b128 v[198:201], v153 offset:50176
	ds_read_b128 v[202:205], v153 offset:51200
	ds_read_b128 v[206:209], v153 offset:52224
	ds_read_b128 v[210:213], v153 offset:53248
	ds_read_b128 v[214:217], v153 offset:54272
	ds_read_b128 v[218:221], v153 offset:55296
	ds_read_b128 v[222:225], v153 offset:56320
	global_load_lds_dwordx4 v[226:227], off
	s_add_i32 m0, s22, 0x2000
	s_add_u32 s20, s20, 0x40080
	v_lshl_add_u64 v[226:227], v[238:239], 0, s[0:1]
	s_addc_u32 s21, s21, 0
	s_add_i32 s22, s53, s37
	global_load_lds_dwordx4 v[226:227], off
	v_lshl_add_u64 v[226:227], s[20:21], 0, v[134:135]
	s_mov_b32 m0, s22
	s_nop 0
	global_load_lds_dwordx4 v[226:227], off
	v_lshl_add_u64 v[226:227], s[20:21], 0, v[0:1]
	s_add_i32 m0, s22, 0x2000
	s_nop 0
	global_load_lds_dwordx4 v[226:227], off
	v_lshl_add_u64 v[226:227], v[240:241], 0, s[0:1]
	s_mov_b32 m0, s42
	s_nop 0
	global_load_lds_dwordx4 v[226:227], off
	v_lshl_add_u64 v[226:227], v[242:243], 0, s[0:1]
	s_mov_b32 m0, s43
	s_nop 0
	global_load_lds_dwordx4 v[226:227], off
	s_waitcnt vmcnt(8)
	s_waitcnt lgkmcnt(0)
	s_barrier
	s_waitcnt lgkmcnt(0)
	v_mfma_f32_16x16x32_bf16 v[64:67], v[142:145], v[194:197], v[64:67]
	v_mfma_f32_16x16x32_bf16 v[56:59], v[170:173], v[194:197], v[56:59]
	v_mfma_f32_16x16x32_bf16 v[48:51], v[142:145], v[202:205], v[48:51]
	v_mfma_f32_16x16x32_bf16 v[40:43], v[170:173], v[202:205], v[40:43]
	v_mfma_f32_16x16x32_bf16 v[32:35], v[142:145], v[210:213], v[32:35]
	v_mfma_f32_16x16x32_bf16 v[24:27], v[170:173], v[210:213], v[24:27]
	v_mfma_f32_16x16x32_bf16 v[16:19], v[142:145], v[218:221], v[16:19]
	v_mfma_f32_16x16x32_bf16 v[8:11], v[170:173], v[218:221], v[8:11]
	v_mfma_f32_16x16x32_bf16 v[64:67], v[166:169], v[198:201], v[64:67]
	v_mfma_f32_16x16x32_bf16 v[56:59], v[174:177], v[198:201], v[56:59]
	v_mfma_f32_16x16x32_bf16 v[48:51], v[166:169], v[206:209], v[48:51]
	v_mfma_f32_16x16x32_bf16 v[40:43], v[174:177], v[206:209], v[40:43]
	v_mfma_f32_16x16x32_bf16 v[32:35], v[166:169], v[214:217], v[32:35]
	v_mfma_f32_16x16x32_bf16 v[24:27], v[174:177], v[214:217], v[24:27]
	v_mfma_f32_16x16x32_bf16 v[16:19], v[166:169], v[222:225], v[16:19]
	v_mfma_f32_16x16x32_bf16 v[8:11], v[174:177], v[222:225], v[8:11]
	v_mfma_f32_16x16x32_bf16 v[60:63], v[178:181], v[194:197], v[60:63]
	v_mfma_f32_16x16x32_bf16 v[52:55], v[186:189], v[194:197], v[52:55]
	v_mfma_f32_16x16x32_bf16 v[44:47], v[178:181], v[202:205], v[44:47]
	v_mfma_f32_16x16x32_bf16 v[36:39], v[186:189], v[202:205], v[36:39]
	v_mfma_f32_16x16x32_bf16 v[28:31], v[178:181], v[210:213], v[28:31]
	v_mfma_f32_16x16x32_bf16 v[20:23], v[186:189], v[210:213], v[20:23]
	v_mfma_f32_16x16x32_bf16 v[12:15], v[178:181], v[218:221], v[12:15]
	v_mfma_f32_16x16x32_bf16 v[4:7], v[186:189], v[218:221], v[4:7]
	v_mfma_f32_16x16x32_bf16 v[60:63], v[182:185], v[198:201], v[60:63]
	v_mfma_f32_16x16x32_bf16 v[52:55], v[190:193], v[198:201], v[52:55]
	v_mfma_f32_16x16x32_bf16 v[44:47], v[182:185], v[206:209], v[44:47]
	v_mfma_f32_16x16x32_bf16 v[36:39], v[190:193], v[206:209], v[36:39]
	v_mfma_f32_16x16x32_bf16 v[28:31], v[182:185], v[214:217], v[28:31]
	v_mfma_f32_16x16x32_bf16 v[20:23], v[190:193], v[214:217], v[20:23]
	v_mfma_f32_16x16x32_bf16 v[12:15], v[182:185], v[222:225], v[12:15]
	v_mfma_f32_16x16x32_bf16 v[4:7], v[190:193], v[222:225], v[4:7]
	s_barrier
	s_add_i32 s51, s51, 2
	s_add_u32 s18, s18, 0x100
	s_addc_u32 s19, s19, 0
	s_add_u32 s49, s49, 0x100
	s_addc_u32 s50, s50, 0
	s_cmp_gt_u32 s51, 13
	s_cbranch_scc0 .LBB0_522
	s_setprio 0
	s_and_b64 vcc, exec, s[8:9]
	s_cbranch_vccz .LBB0_525
	s_barrier

; template <class Epi, class Sched, bool ALIGN_EPI = false, bool SP2 = false>
; __device__ __forceinline__ void gemm_phase(PG8_LAS unsigned char* lds, const Gemm g, const Sched& S, const Epi& E, const int tid) {
;     ...
;         const bool has_next = S.next(ui + 1, nxt);
;         const char* nA = has_next ? (const char*)g.A + (size_t)nxt.pm * tstep : cA; const char* nB = has_next ? (const char*)g.Bt + (size_t)nxt.pn * tstep : cB;
;     ...
; #pragma unroll
;         for (int a = 0; a < 2; ++a)
; #pragma unroll
;             for (int b = 0; b < 2; ++b)
; #pragma unroll
;                 for (int m = 0; m < 4; ++m)
; #pragma unroll
;                     for (int n = 0; n < 2; ++n) acc[a][b][m][n] = (f32x4){0.f, 0.f, 0.f, 0.f};
;         cur = nxt; cA = nA; cB = nB; ++ui;
.LBB0_841:
	s_ashr_i32 s13, s12, 31
	s_lshl_b64 s[14:15], s[12:13], 19
	s_add_u32 s14, s34, s14
	s_addc_u32 s15, s36, s15
	s_and_b64 s[16:17], s[38:39], exec
	s_cselect_b32 s13, s15, s23
	s_cselect_b32 s19, s14, s22
	s_ashr_i32 s11, s10, 31
	s_lshl_b64 s[16:17], s[10:11], 19
	s_add_u32 s16, s4, s16
	s_addc_u32 s17, s5, s17
	s_and_b64 s[26:27], s[38:39], exec
	s_cselect_b32 s11, s17, s25
	s_cselect_b32 s46, s16, s24
	s_add_u32 s22, s22, 0x40080
	s_addc_u32 s23, s23, 0
	s_add_u32 s47, s24, 0x100
	v_mov_b32_e32 v4, 0
	s_addc_u32 s48, s25, 0
	s_mov_b32 s49, -2
	v_mov_b64_e32 v[4:5], 0
	v_mov_b64_e32 v[6:7], 0
	v_mov_b64_e32 v[8:9], 0
	v_mov_b64_e32 v[10:11], 0
	v_mov_b64_e32 v[12:13], 0
	v_mov_b64_e32 v[14:15], 0
	v_mov_b64_e32 v[16:17], 0
	v_mov_b64_e32 v[18:19], 0
	v_mov_b64_e32 v[20:21], 0
	v_mov_b64_e32 v[22:23], 0
	v_mov_b64_e32 v[24:25], 0
	v_mov_b64_e32 v[26:27], 0
	v_mov_b64_e32 v[28:29], 0
	v_mov_b64_e32 v[30:31], 0
	v_mov_b64_e32 v[32:33], 0
	v_mov_b64_e32 v[34:35], 0
	v_mov_b64_e32 v[36:37], 0
	v_mov_b64_e32 v[38:39], 0
	v_mov_b64_e32 v[40:41], 0
	v_mov_b64_e32 v[42:43], 0
	v_mov_b64_e32 v[44:45], 0
	v_mov_b64_e32 v[46:47], 0
	v_mov_b64_e32 v[48:49], 0
	v_mov_b64_e32 v[50:51], 0
	v_mov_b64_e32 v[52:53], 0
	v_mov_b64_e32 v[54:55], 0
	v_mov_b64_e32 v[56:57], 0
	v_mov_b64_e32 v[58:59], 0
	v_mov_b64_e32 v[60:61], 0
	v_mov_b64_e32 v[62:63], 0
	v_mov_b64_e32 v[64:65], 0
	v_mov_b64_e32 v[66:67], 0
	v_mov_b64_e32 v[68:69], 0
	v_mov_b64_e32 v[70:71], 0
	v_mov_b64_e32 v[72:73], 0
	v_mov_b64_e32 v[74:75], 0
	v_mov_b64_e32 v[76:77], 0
	v_mov_b64_e32 v[78:79], 0
	v_mov_b64_e32 v[80:81], 0
	v_mov_b64_e32 v[82:83], 0
	v_mov_b64_e32 v[84:85], 0
	v_mov_b64_e32 v[86:87], 0
	v_mov_b64_e32 v[88:89], 0
	v_mov_b64_e32 v[90:91], 0
	v_mov_b64_e32 v[92:93], 0
	v_mov_b64_e32 v[94:95], 0
	v_mov_b64_e32 v[96:97], 0
	v_mov_b64_e32 v[98:99], 0
	v_mov_b64_e32 v[100:101], 0
	v_mov_b64_e32 v[102:103], 0
	v_mov_b64_e32 v[104:105], 0
	v_mov_b64_e32 v[106:107], 0
	v_mov_b64_e32 v[108:109], 0
	v_mov_b64_e32 v[110:111], 0
	v_mov_b64_e32 v[112:113], 0
	v_mov_b64_e32 v[114:115], 0
	v_mov_b64_e32 v[116:117], 0
	v_mov_b64_e32 v[118:119], 0
	v_mov_b64_e32 v[120:121], 0
	v_mov_b64_e32 v[122:123], 0
	v_mov_b64_e32 v[124:125], 0
	v_mov_b64_e32 v[126:127], 0
	v_mov_b64_e32 v[128:129], 0
	v_mov_b64_e32 v[130:131], 0
	s_cmp_lt_u32 s92, 4
	s_cbranch_scc1 .Lprio_skip4
	s_setprio 1
.Lprio_skip4:
.LBB0_842:
	s_add_u32 s24, s22, 0xfffc0080
	s_addc_u32 s25, s23, -1
	s_add_i32 s50, 0, 0x10000
	s_cmp_eq_u32 s49, 12
	s_cselect_b32 s27, s13, s25
	s_cselect_b32 s26, s19, s24
	v_add_u32_e32 v148, s50, v146
	s_cselect_b32 s25, s11, s48
	s_cselect_b32 s24, s46, s47
	s_add_i32 s52, 0, 0x14000
	ds_read_b128 v[142:145], v148
	ds_read_b128 v[166:169], v148 offset:1024
	ds_read_b128 v[170:173], v148 offset:2048
	ds_read_b128 v[174:177], v148 offset:3072
	v_add_u32_e32 v148, s52, v146
	ds_read_b128 v[178:181], v148
	ds_read_b128 v[182:185], v148 offset:1024
	ds_read_b128 v[186:189], v148 offset:2048
	ds_read_b128 v[190:193], v148 offset:3072
	v_lshl_add_u64 v[226:227], s[22:23], 0, v[138:139]
	s_add_i32 m0, s21, 0xc000
	ds_read_b128 v[194:197], v153
	ds_read_b128 v[198:201], v153 offset:1024
	ds_read_b128 v[202:205], v153 offset:2048
	ds_read_b128 v[206:209], v153 offset:3072
	ds_read_b128 v[210:213], v153 offset:4096
	ds_read_b128 v[214:217], v153 offset:5120
	ds_read_b128 v[218:221], v153 offset:6144
	ds_read_b128 v[222:225], v153 offset:7168
	global_load_lds_dwordx4 v[226:227], off
	v_lshl_add_u64 v[226:227], s[22:23], 0, v[140:141]
	s_add_i32 m0, s21, 0xe000
	s_nop 0
	global_load_lds_dwordx4 v[226:227], off
	s_waitcnt vmcnt(8)
	s_waitcnt lgkmcnt(0)
	s_barrier
	s_waitcnt lgkmcnt(0)
	v_mfma_f32_16x16x32_bf16 v[128:131], v[142:145], v[194:197], v[128:131]
	v_mfma_f32_16x16x32_bf16 v[124:127], v[170:173], v[194:197], v[124:127]
	v_mfma_f32_16x16x32_bf16 v[112:115], v[142:145], v[202:205], v[112:115]
	v_mfma_f32_16x16x32_bf16 v[108:111], v[170:173], v[202:205], v[108:111]
	v_mfma_f32_16x16x32_bf16 v[96:99], v[142:145], v[210:213], v[96:99]
	v_mfma_f32_16x16x32_bf16 v[92:95], v[170:173], v[210:213], v[92:95]
	v_mfma_f32_16x16x32_bf16 v[80:83], v[142:145], v[218:221], v[80:83]
	v_mfma_f32_16x16x32_bf16 v[76:79], v[170:173], v[218:221], v[76:79]
	v_mfma_f32_16x16x32_bf16 v[128:131], v[166:169], v[198:201], v[128:131]
	v_mfma_f32_16x16x32_bf16 v[124:127], v[174:177], v[198:201], v[124:127]
	v_mfma_f32_16x16x32_bf16 v[112:115], v[166:169], v[206:209], v[112:115]
	v_mfma_f32_16x16x32_bf16 v[108:111], v[174:177], v[206:209], v[108:111]
	v_mfma_f32_16x16x32_bf16 v[96:99], v[166:169], v[214:217], v[96:99]
	v_mfma_f32_16x16x32_bf16 v[92:95], v[174:177], v[214:217], v[92:95]
	v_mfma_f32_16x16x32_bf16 v[80:83], v[166:169], v[222:225], v[80:83]
	v_mfma_f32_16x16x32_bf16 v[76:79], v[174:177], v[222:225], v[76:79]
	v_mfma_f32_16x16x32_bf16 v[120:123], v[178:181], v[194:197], v[120:123]
	v_mfma_f32_16x16x32_bf16 v[116:119], v[186:189], v[194:197], v[116:119]
	v_mfma_f32_16x16x32_bf16 v[104:107], v[178:181], v[202:205], v[104:107]
	v_mfma_f32_16x16x32_bf16 v[100:103], v[186:189], v[202:205], v[100:103]
	v_mfma_f32_16x16x32_bf16 v[88:91], v[178:181], v[210:213], v[88:91]
	v_mfma_f32_16x16x32_bf16 v[84:87], v[186:189], v[210:213], v[84:87]
	v_mfma_f32_16x16x32_bf16 v[72:75], v[178:181], v[218:221], v[72:75]
	v_mfma_f32_16x16x32_bf16 v[68:71], v[186:189], v[218:221], v[68:71]
	v_mfma_f32_16x16x32_bf16 v[120:123], v[182:185], v[198:201], v[120:123]
	v_mfma_f32_16x16x32_bf16 v[116:119], v[190:193], v[198:201], v[116:119]
	v_mfma_f32_16x16x32_bf16 v[104:107], v[182:185], v[206:209], v[104:107]
	v_mfma_f32_16x16x32_bf16 v[100:103], v[190:193], v[206:209], v[100:103]
	v_mfma_f32_16x16x32_bf16 v[88:91], v[182:185], v[214:217], v[88:91]
	v_mfma_f32_16x16x32_bf16 v[84:87], v[190:193], v[214:217], v[84:87]
	v_mfma_f32_16x16x32_bf16 v[72:75], v[182:185], v[222:225], v[72:75]
	v_mfma_f32_16x16x32_bf16 v[68:71], v[190:193], v[222:225], v[68:71]
	s_barrier
; #define PG8_STAGE(bufoff, gbase, voff) do { _Pragma("unroll") for (int _i = 0; _i < 2; ++_i) \
;         __builtin_amdgcn_global_load_lds((const unsigned*)((const char*)(gbase) + (voff)[_i]), (PG8_LAS unsigned*)(lds + (bufoff) + ldsw + _i * 8192), 16, 0, 0); } while (0)
; #define PG8_LDA(dst, b, h) do { _Pragma("unroll") for (int m = 0; m < 4; ++m) _Pragma("unroll") for (int k = 0; k < 2; ++k) dst[m][k] = *(const PG8_LAS bf16x8*)(lds + PG8_SA(b, h) + aoff + m * 2048 + k * 1024); } while (0)
; #define PG8_LDB(dst, b, h) do { _Pragma("unroll") for (int n = 0; n < 2; ++n) _Pragma("unroll") for (int k = 0; k < 2; ++k) dst[n][k] = *(const PG8_LAS bf16x8*)(lds + PG8_SB(b, h) + boff + n * 2048 + k * 1024); } while (0)
; #define PG8_MMA(ai, bj, At, Bt) do { __builtin_amdgcn_s_setprio(1); _Pragma("unroll") for (int m = 0; m < 4; ++m) _Pragma("unroll") for (int n = 0; n < 2; ++n) _Pragma("unroll") for (int k = 0; k < 2; ++k) \
;         acc[ai][bj][m][n] = __builtin_amdgcn_mfma_f32_16x16x32_bf16(Bt[n][k], At[m][k], acc[ai][bj][m][n], 0, 0, 0); __builtin_amdgcn_s_setprio(0); } while (0)
; #define PG8_WAIT_V(n) asm volatile("s_waitcnt vmcnt(" #n ")" ::: "memory")
; #define PG8_WAIT_L(n) asm volatile("s_waitcnt lgkmcnt(" #n ")" ::: "memory")
; #define PG8_BAR __builtin_amdgcn_s_barrier()
; #define PG8_SCHED __builtin_amdgcn_sched_barrier(0)
; template <class Epi, class Sched, bool ALIGN_EPI = false, bool SP2 = false>
; __device__ __forceinline__ void gemm_phase(PG8_LAS unsigned char* lds, const Gemm g, const Sched& S, const Epi& E, const int tid) {
;     ...
;             PG8_WAIT_V(8); PG8_WAIT_L(0); PG8_BAR; PG8_MMA(0, 0, At, B0); PG8_MMA(0, 1, At, B1); PG8_BAR; PG8_SCHED;
;             PG8_LDA(At, 0, 1); PG8_STAGE(PG8_SB(0, 0), b2, voffB); PG8_STAGE(PG8_SB(0, 1), b2 + hstep, voffB); PG8_STAGE(PG8_SA(0, 0), a2, voffA);
;             PG8_WAIT_V(8); PG8_WAIT_L(0); PG8_BAR; PG8_MMA(1, 0, At, B0); PG8_MMA(1, 1, At, B1); PG8_BAR; PG8_SCHED;
;             PG8_LDB(B0, 1, 0); PG8_LDB(B1, 1, 1); PG8_SCHED; PG8_LDA(At, 1, 0); PG8_STAGE(PG8_SA(0, 1), a2 + hstep, voffA);
;             PG8_WAIT_V(8); PG8_WAIT_L(0); PG8_BAR; PG8_MMA(0, 0, At, B0); PG8_MMA(0, 1, At, B1); PG8_BAR; PG8_SCHED;
	s_add_i32 s50, s50, s37
	v_lshl_add_u64 v[226:227], s[24:25], 0, v[132:133]
	s_mov_b32 m0, s50
	ds_read_b128 v[194:197], v153 offset:16384
	ds_read_b128 v[198:201], v153 offset:17408
	ds_read_b128 v[202:205], v153 offset:18432
	ds_read_b128 v[206:209], v153 offset:19456
	ds_read_b128 v[210:213], v153 offset:20480
	ds_read_b128 v[214:217], v153 offset:21504
	ds_read_b128 v[218:221], v153 offset:22528
	ds_read_b128 v[222:225], v153 offset:23552
	global_load_lds_dwordx4 v[226:227], off
	s_add_i32 m0, s50, 0x2000
	s_add_u32 s50, s24, 0x40000
	v_lshl_add_u64 v[238:239], s[24:25], 0, v[136:137]
	s_addc_u32 s51, s25, 0
	s_add_i32 s52, s52, s37
	global_load_lds_dwordx4 v[238:239], off
	v_lshl_add_u64 v[240:241], s[50:51], 0, v[132:133]
	s_mov_b32 m0, s52
	v_lshl_add_u64 v[242:243], s[26:27], 0, v[134:135]
	global_load_lds_dwordx4 v[240:241], off
	v_lshl_add_u64 v[240:241], s[50:51], 0, v[136:137]
	s_add_i32 m0, s52, 0x2000
	s_nop 0
	global_load_lds_dwordx4 v[240:241], off
	v_lshl_add_u64 v[240:241], s[26:27], 0, v[0:1]
	s_mov_b32 m0, s21
	s_nop 0
	global_load_lds_dwordx4 v[240:241], off
	s_mov_b32 m0, s40
	s_nop 0
	global_load_lds_dwordx4 v[242:243], off
	s_waitcnt vmcnt(8)
	s_waitcnt lgkmcnt(0)
	s_barrier
	s_waitcnt lgkmcnt(0)
	v_mfma_f32_16x16x32_bf16 v[64:67], v[142:145], v[194:197], v[64:67]
	v_mfma_f32_16x16x32_bf16 v[60:63], v[170:173], v[194:197], v[60:63]
	v_mfma_f32_16x16x32_bf16 v[48:51], v[142:145], v[202:205], v[48:51]
	v_mfma_f32_16x16x32_bf16 v[44:47], v[170:173], v[202:205], v[44:47]
	v_mfma_f32_16x16x32_bf16 v[32:35], v[142:145], v[210:213], v[32:35]
	v_mfma_f32_16x16x32_bf16 v[28:31], v[170:173], v[210:213], v[28:31]
	v_mfma_f32_16x16x32_bf16 v[16:19], v[142:145], v[218:221], v[16:19]
	v_mfma_f32_16x16x32_bf16 v[12:15], v[170:173], v[218:221], v[12:15]
	v_mfma_f32_16x16x32_bf16 v[64:67], v[166:169], v[198:201], v[64:67]
	v_mfma_f32_16x16x32_bf16 v[60:63], v[174:177], v[198:201], v[60:63]
	v_mfma_f32_16x16x32_bf16 v[48:51], v[166:169], v[206:209], v[48:51]
	v_mfma_f32_16x16x32_bf16 v[44:47], v[174:177], v[206:209], v[44:47]
	v_mfma_f32_16x16x32_bf16 v[32:35], v[166:169], v[214:217], v[32:35]
	v_mfma_f32_16x16x32_bf16 v[28:31], v[174:177], v[214:217], v[28:31]
	v_mfma_f32_16x16x32_bf16 v[16:19], v[166:169], v[222:225], v[16:19]
	v_mfma_f32_16x16x32_bf16 v[12:15], v[174:177], v[222:225], v[12:15]
	v_mfma_f32_16x16x32_bf16 v[56:59], v[178:181], v[194:197], v[56:59]
	v_mfma_f32_16x16x32_bf16 v[52:55], v[186:189], v[194:197], v[52:55]
	v_mfma_f32_16x16x32_bf16 v[40:43], v[178:181], v[202:205], v[40:43]
	v_mfma_f32_16x16x32_bf16 v[36:39], v[186:189], v[202:205], v[36:39]
	v_mfma_f32_16x16x32_bf16 v[24:27], v[178:181], v[210:213], v[24:27]
	v_mfma_f32_16x16x32_bf16 v[20:23], v[186:189], v[210:213], v[20:23]
	v_mfma_f32_16x16x32_bf16 v[8:11], v[178:181], v[218:221], v[8:11]
	v_mfma_f32_16x16x32_bf16 v[4:7], v[186:189], v[218:221], v[4:7]
	v_mfma_f32_16x16x32_bf16 v[56:59], v[182:185], v[198:201], v[56:59]
	v_mfma_f32_16x16x32_bf16 v[52:55], v[190:193], v[198:201], v[52:55]
	v_mfma_f32_16x16x32_bf16 v[40:43], v[182:185], v[206:209], v[40:43]
	v_mfma_f32_16x16x32_bf16 v[36:39], v[190:193], v[206:209], v[36:39]
	v_mfma_f32_16x16x32_bf16 v[24:27], v[182:185], v[214:217], v[24:27]
	v_mfma_f32_16x16x32_bf16 v[20:23], v[190:193], v[214:217], v[20:23]
	v_mfma_f32_16x16x32_bf16 v[8:11], v[182:185], v[222:225], v[8:11]
	v_mfma_f32_16x16x32_bf16 v[4:7], v[190:193], v[222:225], v[4:7]
	s_barrier
	s_add_i32 s50, 0, 0x18000
	v_add_u32_e32 v148, s50, v146
	s_add_i32 s51, 0, 0x1c000
	ds_read_b128 v[142:145], v148
	ds_read_b128 v[166:169], v148 offset:1024
	ds_read_b128 v[170:173], v148 offset:2048
	ds_read_b128 v[174:177], v148 offset:3072
	v_add_u32_e32 v148, s51, v146
	ds_read_b128 v[178:181], v148
	ds_read_b128 v[182:185], v148 offset:1024
	ds_read_b128 v[186:189], v148 offset:2048
	ds_read_b128 v[190:193], v148 offset:3072
	s_add_u32 s26, s26, 0x40000
	s_addc_u32 s27, s27, 0
	s_mov_b32 m0, s41
	v_lshl_add_u64 v[244:245], s[26:27], 0, v[0:1]
	ds_read_b128 v[194:197], v153 offset:32768
	ds_read_b128 v[198:201], v153 offset:33792
	ds_read_b128 v[202:205], v153 offset:34816
	ds_read_b128 v[206:209], v153 offset:35840
	ds_read_b128 v[210:213], v153 offset:36864
	ds_read_b128 v[214:217], v153 offset:37888
	ds_read_b128 v[218:221], v153 offset:38912
	ds_read_b128 v[222:225], v153 offset:39936
	global_load_lds_dwordx4 v[244:245], off
	v_lshl_add_u64 v[244:245], s[26:27], 0, v[134:135]
	s_mov_b32 m0, s42
	s_nop 0
	global_load_lds_dwordx4 v[244:245], off
	s_waitcnt vmcnt(8)
	s_waitcnt lgkmcnt(0)
	s_barrier
; #define PG8_STAGE(bufoff, gbase, voff) do { _Pragma("unroll") for (int _i = 0; _i < 2; ++_i) \
;         __builtin_amdgcn_global_load_lds((const unsigned*)((const char*)(gbase) + (voff)[_i]), (PG8_LAS unsigned*)(lds + (bufoff) + ldsw + _i * 8192), 16, 0, 0); } while (0)
; #define PG8_LDA(dst, b, h) do { _Pragma("unroll") for (int m = 0; m < 4; ++m) _Pragma("unroll") for (int k = 0; k < 2; ++k) dst[m][k] = *(const PG8_LAS bf16x8*)(lds + PG8_SA(b, h) + aoff + m * 2048 + k * 1024); } while (0)
; #define PG8_LDB(dst, b, h) do { _Pragma("unroll") for (int n = 0; n < 2; ++n) _Pragma("unroll") for (int k = 0; k < 2; ++k) dst[n][k] = *(const PG8_LAS bf16x8*)(lds + PG8_SB(b, h) + boff + n * 2048 + k * 1024); } while (0)
; #define PG8_MMA(ai, bj, At, Bt) do { __builtin_amdgcn_s_setprio(1); _Pragma("unroll") for (int m = 0; m < 4; ++m) _Pragma("unroll") for (int n = 0; n < 2; ++n) _Pragma("unroll") for (int k = 0; k < 2; ++k) \
;         acc[ai][bj][m][n] = __builtin_amdgcn_mfma_f32_16x16x32_bf16(Bt[n][k], At[m][k], acc[ai][bj][m][n], 0, 0, 0); __builtin_amdgcn_s_setprio(0); } while (0)
; #define PG8_WAIT_V(n) asm volatile("s_waitcnt vmcnt(" #n ")" ::: "memory")
; #define PG8_WAIT_L(n) asm volatile("s_waitcnt lgkmcnt(" #n ")" ::: "memory")
; template <class Epi, class Sched, bool ALIGN_EPI = false, bool SP2 = false>
; __device__ __forceinline__ void gemm_phase(PG8_LAS unsigned char* lds, const Gemm g, const Sched& S, const Epi& E, const int tid) {
;     ...
;             PG8_WAIT_V(8); PG8_WAIT_L(0); PG8_BAR; PG8_MMA(0, 0, At, B0); PG8_MMA(0, 1, At, B1); PG8_BAR; PG8_SCHED;
;             PG8_LDA(At, 0, 1); PG8_STAGE(PG8_SB(0, 0), b2, voffB); PG8_STAGE(PG8_SB(0, 1), b2 + hstep, voffB); PG8_STAGE(PG8_SA(0, 0), a2, voffA);
;             PG8_WAIT_V(8); PG8_WAIT_L(0); PG8_BAR; PG8_MMA(1, 0, At, B0); PG8_MMA(1, 1, At, B1); PG8_BAR; PG8_SCHED;
;             PG8_LDB(B0, 1, 0); PG8_LDB(B1, 1, 1); PG8_SCHED; PG8_LDA(At, 1, 0); PG8_STAGE(PG8_SA(0, 1), a2 + hstep, voffA);
;             PG8_WAIT_V(8); PG8_WAIT_L(0); PG8_BAR; PG8_MMA(0, 0, At, B0); PG8_MMA(0, 1, At, B1); PG8_BAR; PG8_SCHED;
;             PG8_LDA(At, 1, 1); PG8_STAGE(PG8_SB(1, 0), b3, voffB); PG8_STAGE(PG8_SB(1, 1), b3 + hstep, voffB); PG8_STAGE(PG8_SA(1, 0), a3, voffA);
;             PG8_WAIT_V(8); PG8_WAIT_L(0); PG8_BAR; PG8_MMA(1, 0, At, B0); PG8_MMA(1, 1, At, B1); PG8_BAR; PG8_SCHED;
	s_waitcnt lgkmcnt(0)
	v_mfma_f32_16x16x32_bf16 v[128:131], v[142:145], v[194:197], v[128:131]
	v_mfma_f32_16x16x32_bf16 v[124:127], v[170:173], v[194:197], v[124:127]
	v_mfma_f32_16x16x32_bf16 v[112:115], v[142:145], v[202:205], v[112:115]
	v_mfma_f32_16x16x32_bf16 v[108:111], v[170:173], v[202:205], v[108:111]
	v_mfma_f32_16x16x32_bf16 v[96:99], v[142:145], v[210:213], v[96:99]
	v_mfma_f32_16x16x32_bf16 v[92:95], v[170:173], v[210:213], v[92:95]
	v_mfma_f32_16x16x32_bf16 v[80:83], v[142:145], v[218:221], v[80:83]
	v_mfma_f32_16x16x32_bf16 v[76:79], v[170:173], v[218:221], v[76:79]
	v_mfma_f32_16x16x32_bf16 v[128:131], v[166:169], v[198:201], v[128:131]
	v_mfma_f32_16x16x32_bf16 v[124:127], v[174:177], v[198:201], v[124:127]
	v_mfma_f32_16x16x32_bf16 v[112:115], v[166:169], v[206:209], v[112:115]
	v_mfma_f32_16x16x32_bf16 v[108:111], v[174:177], v[206:209], v[108:111]
	v_mfma_f32_16x16x32_bf16 v[96:99], v[166:169], v[214:217], v[96:99]
	v_mfma_f32_16x16x32_bf16 v[92:95], v[174:177], v[214:217], v[92:95]
	v_mfma_f32_16x16x32_bf16 v[80:83], v[166:169], v[222:225], v[80:83]
	v_mfma_f32_16x16x32_bf16 v[76:79], v[174:177], v[222:225], v[76:79]
	v_mfma_f32_16x16x32_bf16 v[120:123], v[178:181], v[194:197], v[120:123]
	v_mfma_f32_16x16x32_bf16 v[116:119], v[186:189], v[194:197], v[116:119]
	v_mfma_f32_16x16x32_bf16 v[104:107], v[178:181], v[202:205], v[104:107]
	v_mfma_f32_16x16x32_bf16 v[100:103], v[186:189], v[202:205], v[100:103]
	v_mfma_f32_16x16x32_bf16 v[88:91], v[178:181], v[210:213], v[88:91]
	v_mfma_f32_16x16x32_bf16 v[84:87], v[186:189], v[210:213], v[84:87]
	v_mfma_f32_16x16x32_bf16 v[72:75], v[178:181], v[218:221], v[72:75]
	v_mfma_f32_16x16x32_bf16 v[68:71], v[186:189], v[218:221], v[68:71]
	v_mfma_f32_16x16x32_bf16 v[120:123], v[182:185], v[198:201], v[120:123]
	v_mfma_f32_16x16x32_bf16 v[116:119], v[190:193], v[198:201], v[116:119]
	v_mfma_f32_16x16x32_bf16 v[104:107], v[182:185], v[206:209], v[104:107]
	v_mfma_f32_16x16x32_bf16 v[100:103], v[190:193], v[206:209], v[100:103]
	v_mfma_f32_16x16x32_bf16 v[88:91], v[182:185], v[214:217], v[88:91]
	v_mfma_f32_16x16x32_bf16 v[84:87], v[190:193], v[214:217], v[84:87]
	v_mfma_f32_16x16x32_bf16 v[72:75], v[182:185], v[222:225], v[72:75]
	v_mfma_f32_16x16x32_bf16 v[68:71], v[190:193], v[222:225], v[68:71]
	s_barrier
	s_add_i32 s26, s50, s37
	v_lshl_add_u64 v[226:227], v[226:227], 0, s[0:1]
	s_mov_b32 m0, s26
	ds_read_b128 v[194:197], v153 offset:49152
	ds_read_b128 v[198:201], v153 offset:50176
	ds_read_b128 v[202:205], v153 offset:51200
	ds_read_b128 v[206:209], v153 offset:52224
	ds_read_b128 v[210:213], v153 offset:53248
	ds_read_b128 v[214:217], v153 offset:54272
	ds_read_b128 v[218:221], v153 offset:55296
	ds_read_b128 v[222:225], v153 offset:56320
	global_load_lds_dwordx4 v[226:227], off
	s_add_i32 m0, s26, 0x2000
	s_add_u32 s24, s24, 0x40080
	v_lshl_add_u64 v[226:227], v[238:239], 0, s[0:1]
	s_addc_u32 s25, s25, 0
	s_add_i32 s26, s51, s37
	global_load_lds_dwordx4 v[226:227], off
	v_lshl_add_u64 v[226:227], s[24:25], 0, v[132:133]
	s_mov_b32 m0, s26
	s_nop 0
	global_load_lds_dwordx4 v[226:227], off
	v_lshl_add_u64 v[226:227], s[24:25], 0, v[136:137]
	s_add_i32 m0, s26, 0x2000
	s_nop 0
	global_load_lds_dwordx4 v[226:227], off
	v_lshl_add_u64 v[226:227], v[240:241], 0, s[0:1]
	s_mov_b32 m0, s43
	s_nop 0
	global_load_lds_dwordx4 v[226:227], off
	v_lshl_add_u64 v[226:227], v[242:243], 0, s[0:1]
	s_mov_b32 m0, s44
	s_nop 0
	global_load_lds_dwordx4 v[226:227], off
	s_waitcnt vmcnt(8)
	s_waitcnt lgkmcnt(0)
	s_barrier
	s_waitcnt lgkmcnt(0)
	v_mfma_f32_16x16x32_bf16 v[64:67], v[142:145], v[194:197], v[64:67]
	v_mfma_f32_16x16x32_bf16 v[60:63], v[170:173], v[194:197], v[60:63]
	v_mfma_f32_16x16x32_bf16 v[48:51], v[142:145], v[202:205], v[48:51]
	v_mfma_f32_16x16x32_bf16 v[44:47], v[170:173], v[202:205], v[44:47]
	v_mfma_f32_16x16x32_bf16 v[32:35], v[142:145], v[210:213], v[32:35]
	v_mfma_f32_16x16x32_bf16 v[28:31], v[170:173], v[210:213], v[28:31]
	v_mfma_f32_16x16x32_bf16 v[16:19], v[142:145], v[218:221], v[16:19]
	v_mfma_f32_16x16x32_bf16 v[12:15], v[170:173], v[218:221], v[12:15]
	v_mfma_f32_16x16x32_bf16 v[64:67], v[166:169], v[198:201], v[64:67]
	v_mfma_f32_16x16x32_bf16 v[60:63], v[174:177], v[198:201], v[60:63]
	v_mfma_f32_16x16x32_bf16 v[48:51], v[166:169], v[206:209], v[48:51]
	v_mfma_f32_16x16x32_bf16 v[44:47], v[174:177], v[206:209], v[44:47]
	v_mfma_f32_16x16x32_bf16 v[32:35], v[166:169], v[214:217], v[32:35]
	v_mfma_f32_16x16x32_bf16 v[28:31], v[174:177], v[214:217], v[28:31]
	v_mfma_f32_16x16x32_bf16 v[16:19], v[166:169], v[222:225], v[16:19]
	v_mfma_f32_16x16x32_bf16 v[12:15], v[174:177], v[222:225], v[12:15]
	v_mfma_f32_16x16x32_bf16 v[56:59], v[178:181], v[194:197], v[56:59]
	v_mfma_f32_16x16x32_bf16 v[52:55], v[186:189], v[194:197], v[52:55]
	v_mfma_f32_16x16x32_bf16 v[40:43], v[178:181], v[202:205], v[40:43]
	v_mfma_f32_16x16x32_bf16 v[36:39], v[186:189], v[202:205], v[36:39]
	v_mfma_f32_16x16x32_bf16 v[24:27], v[178:181], v[210:213], v[24:27]
	v_mfma_f32_16x16x32_bf16 v[20:23], v[186:189], v[210:213], v[20:23]
	v_mfma_f32_16x16x32_bf16 v[8:11], v[178:181], v[218:221], v[8:11]
	v_mfma_f32_16x16x32_bf16 v[4:7], v[186:189], v[218:221], v[4:7]
	v_mfma_f32_16x16x32_bf16 v[56:59], v[182:185], v[198:201], v[56:59]
	v_mfma_f32_16x16x32_bf16 v[52:55], v[190:193], v[198:201], v[52:55]
	v_mfma_f32_16x16x32_bf16 v[40:43], v[182:185], v[206:209], v[40:43]
	v_mfma_f32_16x16x32_bf16 v[36:39], v[190:193], v[206:209], v[36:39]
	v_mfma_f32_16x16x32_bf16 v[24:27], v[182:185], v[214:217], v[24:27]
	v_mfma_f32_16x16x32_bf16 v[20:23], v[190:193], v[214:217], v[20:23]
	v_mfma_f32_16x16x32_bf16 v[8:11], v[182:185], v[222:225], v[8:11]
	v_mfma_f32_16x16x32_bf16 v[4:7], v[190:193], v[222:225], v[4:7]
	s_barrier
	s_add_i32 s49, s49, 2
	s_add_u32 s22, s22, 0x100
	s_addc_u32 s23, s23, 0
	s_add_u32 s47, s47, 0x100
	s_addc_u32 s48, s48, 0
	s_cmp_gt_u32 s49, 13
	s_cbranch_scc0 .LBB0_842
	s_setprio 0
	s_and_b64 vcc, exec, s[8:9]
	s_cbranch_vccz .LBB0_845
	s_barrier
